# stack of the individually neutral edits on v26: sigmoid epilogue packed ops, nt weight loads, redundant lgkmcnt waits removed, loop-edge rotation in 4 GEMM loops
# baseline (speedup 1.0000x reference)
; #define PG8_STAGE(bufoff, gbase, voff) do { _Pragma("unroll") for (int _i = 0; _i < 2; ++_i) \
;         __builtin_amdgcn_global_load_lds((const unsigned*)((const char*)(gbase) + (voff)[_i]), (PG8_LAS unsigned*)(lds + (bufoff) + ldsw + _i * 8192), 16, 0, 0); } while (0)
; #define PG8_LDA(dst, b, h) do { _Pragma("unroll") for (int m = 0; m < 4; ++m) _Pragma("unroll") for (int k = 0; k < 2; ++k) dst[m][k] = *(const PG8_LAS bf16x8*)(lds + PG8_SA(b, h) + aoff + m * 2048 + k * 1024); } while (0)
; #define PG8_LDB(dst, b, h) do { _Pragma("unroll") for (int n = 0; n < 2; ++n) _Pragma("unroll") for (int k = 0; k < 2; ++k) dst[n][k] = *(const PG8_LAS bf16x8*)(lds + PG8_SB(b, h) + boff + n * 2048 + k * 1024); } while (0)
; #define PG8_MMA(ai, bj, At, Bt) do { __builtin_amdgcn_s_setprio(1); _Pragma("unroll") for (int m = 0; m < 4; ++m) _Pragma("unroll") for (int n = 0; n < 2; ++n) _Pragma("unroll") for (int k = 0; k < 2; ++k) \
;         acc[ai][bj][m][n] = __builtin_amdgcn_mfma_f32_16x16x32_bf16(Bt[n][k], At[m][k], acc[ai][bj][m][n], 0, 0, 0); __builtin_amdgcn_s_setprio(0); } while (0)
; #define PG8_WAIT_V(n) asm volatile("s_waitcnt vmcnt(" #n ")" ::: "memory")
; #define PG8_WAIT_L(n) asm volatile("s_waitcnt lgkmcnt(" #n ")" ::: "memory")
; #define PG8_BAR __builtin_amdgcn_s_barrier()
; #define PG8_SCHED __builtin_amdgcn_sched_barrier(0)
; template <class Epi, class Sched, bool ALIGN_EPI = false, bool SP2 = false>
; __device__ __forceinline__ void gemm_phase(PG8_LAS unsigned char* lds, const Gemm g, const Sched& S, const Epi& E) {
;     ...
;             PG8_LDB(B0, 0, 0); PG8_LDB(B1, 0, 1); PG8_SCHED; PG8_LDA(At, 0, 0); PG8_STAGE(PG8_SA(1, 1), a1 + hstepA, voffA);
;             PG8_WAIT_V(8); PG8_WAIT_L(0); PG8_BAR; PG8_MMA(0, 0, At, B0); PG8_MMA(0, 1, At, B1); PG8_BAR; PG8_SCHED;
;             PG8_LDA(At, 0, 1); PG8_STAGE(PG8_SB(0, 0), b2, voffB); PG8_STAGE(PG8_SB(0, 1), b2 + hstepB, voffB); PG8_STAGE(PG8_SA(0, 0), a2, voffA);
.Lgk_146:
	ds_read_b128 v[164:167], v130
	ds_read_b128 v[168:171], v130 offset:1024
	ds_read_b128 v[186:189], v130 offset:2048
	ds_read_b128 v[190:193], v130 offset:3072
	v_add_u32_e32 v130, s81, v161
	ds_read_b128 v[198:201], v130
	ds_read_b128 v[202:205], v130 offset:1024
	ds_read_b128 v[206:209], v130 offset:2048
	ds_read_b128 v[210:213], v130 offset:3072
	v_lshl_add_u64 v[172:173], s[46:47], 0, v[156:157]
	s_add_i32 m0, s9, 0xc000
	ds_read_b128 v[214:217], v163
	ds_read_b128 v[218:221], v163 offset:1024
	ds_read_b128 v[222:225], v163 offset:2048
	ds_read_b128 v[226:229], v163 offset:3072
	ds_read_b128 v[230:233], v163 offset:4096
	ds_read_b128 v[234:237], v163 offset:5120
	ds_read_b128 v[238:241], v163 offset:6144
	ds_read_b128 v[242:245], v163 offset:7168
	global_load_lds_dwordx4 v[172:173], off
	v_lshl_add_u64 v[172:173], s[46:47], 0, v[158:159]
	s_add_i32 m0, s9, 0xe000
	s_nop 0
	global_load_lds_dwordx4 v[172:173], off
	s_waitcnt vmcnt(8)
	s_waitcnt lgkmcnt(0)
	s_barrier
	s_setprio 1
	v_mfma_f32_16x16x32_bf16 v[126:129], v[164:167], v[214:217], v[126:129]
	v_mfma_f32_16x16x32_bf16 v[122:125], v[186:189], v[214:217], v[122:125]
	v_mfma_f32_16x16x32_bf16 v[118:121], v[164:167], v[222:225], v[118:121]
	v_mfma_f32_16x16x32_bf16 v[114:117], v[186:189], v[222:225], v[114:117]
	v_mfma_f32_16x16x32_bf16 v[102:105], v[164:167], v[230:233], v[102:105]
	v_mfma_f32_16x16x32_bf16 v[98:101], v[186:189], v[230:233], v[98:101]
	v_mfma_f32_16x16x32_bf16 v[86:89], v[164:167], v[238:241], v[86:89]
	v_mfma_f32_16x16x32_bf16 v[82:85], v[186:189], v[238:241], v[82:85]
	v_mfma_f32_16x16x32_bf16 v[126:129], v[168:171], v[218:221], v[126:129]
	v_mfma_f32_16x16x32_bf16 v[122:125], v[190:193], v[218:221], v[122:125]
	v_mfma_f32_16x16x32_bf16 v[118:121], v[168:171], v[226:229], v[118:121]
	v_mfma_f32_16x16x32_bf16 v[114:117], v[190:193], v[226:229], v[114:117]
	v_mfma_f32_16x16x32_bf16 v[102:105], v[168:171], v[234:237], v[102:105]
	v_mfma_f32_16x16x32_bf16 v[98:101], v[190:193], v[234:237], v[98:101]
	v_mfma_f32_16x16x32_bf16 v[86:89], v[168:171], v[242:245], v[86:89]
	v_mfma_f32_16x16x32_bf16 v[82:85], v[190:193], v[242:245], v[82:85]
	s_setprio 0
	s_setprio 1
	v_mfma_f32_16x16x32_bf16 v[110:113], v[198:201], v[214:217], v[110:113]
	v_mfma_f32_16x16x32_bf16 v[106:109], v[206:209], v[214:217], v[106:109]
	v_mfma_f32_16x16x32_bf16 v[94:97], v[198:201], v[222:225], v[94:97]
	v_mfma_f32_16x16x32_bf16 v[90:93], v[206:209], v[222:225], v[90:93]
	v_mfma_f32_16x16x32_bf16 v[78:81], v[198:201], v[230:233], v[78:81]
	v_mfma_f32_16x16x32_bf16 v[74:77], v[206:209], v[230:233], v[74:77]
	v_mfma_f32_16x16x32_bf16 v[70:73], v[198:201], v[238:241], v[70:73]
	v_mfma_f32_16x16x32_bf16 v[66:69], v[206:209], v[238:241], v[66:69]
	v_mfma_f32_16x16x32_bf16 v[110:113], v[202:205], v[218:221], v[110:113]
	v_mfma_f32_16x16x32_bf16 v[106:109], v[210:213], v[218:221], v[106:109]
	v_mfma_f32_16x16x32_bf16 v[94:97], v[202:205], v[226:229], v[94:97]
	v_mfma_f32_16x16x32_bf16 v[90:93], v[210:213], v[226:229], v[90:93]
	v_mfma_f32_16x16x32_bf16 v[78:81], v[202:205], v[234:237], v[78:81]
	v_mfma_f32_16x16x32_bf16 v[74:77], v[210:213], v[234:237], v[74:77]
	v_mfma_f32_16x16x32_bf16 v[70:73], v[202:205], v[242:245], v[70:73]
	v_mfma_f32_16x16x32_bf16 v[66:69], v[210:213], v[242:245], v[66:69]
	s_setprio 0
	s_barrier
	s_add_i32 s10, s69, s8
	v_lshl_add_u64 v[172:173], s[48:49], 0, v[0:1]
	s_mov_b32 m0, s10
	ds_read_b128 v[214:217], v163 offset:16384
	ds_read_b128 v[218:221], v163 offset:17408
	ds_read_b128 v[222:225], v163 offset:18432
	ds_read_b128 v[226:229], v163 offset:19456
	ds_read_b128 v[230:233], v163 offset:20480
	ds_read_b128 v[234:237], v163 offset:21504
	ds_read_b128 v[238:241], v163 offset:22528
	ds_read_b128 v[242:245], v163 offset:23552
	global_load_lds_dwordx4 v[172:173], off
	s_add_i32 m0, s10, 0x2000
	s_add_u32 s10, s48, 0x40000
	v_lshl_add_u64 v[246:247], s[48:49], 0, v[150:151]
	s_addc_u32 s11, s49, 0
	s_add_i32 s69, s81, s8
	global_load_lds_dwordx4 v[246:247], off
	v_lshl_add_u64 v[248:249], s[10:11], 0, v[0:1]
	s_mov_b32 m0, s69
	v_lshl_add_u64 v[130:131], s[50:51], 0, v[152:153]
	global_load_lds_dwordx4 v[248:249], off
	v_lshl_add_u64 v[248:249], s[10:11], 0, v[150:151]
	s_add_i32 m0, s69, 0x2000
	s_nop 0
	global_load_lds_dwordx4 v[248:249], off
	v_lshl_add_u64 v[248:249], s[50:51], 0, v[154:155]
	s_mov_b32 m0, s9
	s_nop 0
	global_load_lds_dwordx4 v[248:249], off
	s_mov_b32 m0, s30
	s_nop 0
	global_load_lds_dwordx4 v[130:131], off
	s_waitcnt vmcnt(8)
	s_waitcnt lgkmcnt(0)
	s_barrier
; #define PG8_STAGE(bufoff, gbase, voff) do { _Pragma("unroll") for (int _i = 0; _i < 2; ++_i) \
;         __builtin_amdgcn_global_load_lds((const unsigned*)((const char*)(gbase) + (voff)[_i]), (PG8_LAS unsigned*)(lds + (bufoff) + ldsw + _i * 8192), 16, 0, 0); } while (0)
; #define PG8_LDA(dst, b, h) do { _Pragma("unroll") for (int m = 0; m < 4; ++m) _Pragma("unroll") for (int k = 0; k < 2; ++k) dst[m][k] = *(const PG8_LAS bf16x8*)(lds + PG8_SA(b, h) + aoff + m * 2048 + k * 1024); } while (0)
; #define PG8_LDB(dst, b, h) do { _Pragma("unroll") for (int n = 0; n < 2; ++n) _Pragma("unroll") for (int k = 0; k < 2; ++k) dst[n][k] = *(const PG8_LAS bf16x8*)(lds + PG8_SB(b, h) + boff + n * 2048 + k * 1024); } while (0)
; #define PG8_MMA(ai, bj, At, Bt) do { __builtin_amdgcn_s_setprio(1); _Pragma("unroll") for (int m = 0; m < 4; ++m) _Pragma("unroll") for (int n = 0; n < 2; ++n) _Pragma("unroll") for (int k = 0; k < 2; ++k) \
;         acc[ai][bj][m][n] = __builtin_amdgcn_mfma_f32_16x16x32_bf16(Bt[n][k], At[m][k], acc[ai][bj][m][n], 0, 0, 0); __builtin_amdgcn_s_setprio(0); } while (0)
; #define PG8_WAIT_V(n) asm volatile("s_waitcnt vmcnt(" #n ")" ::: "memory")
; #define PG8_WAIT_L(n) asm volatile("s_waitcnt lgkmcnt(" #n ")" ::: "memory")
; #define PG8_BAR __builtin_amdgcn_s_barrier()
; #define PG8_SCHED __builtin_amdgcn_sched_barrier(0)
; template <class Epi, class Sched, bool ALIGN_EPI = false, bool SP2 = false>
; __device__ __forceinline__ void gemm_phase(PG8_LAS unsigned char* lds, const Gemm g, const Sched& S, const Epi& E) {
;     ...
;             PG8_WAIT_V(8); PG8_WAIT_L(0); PG8_BAR; PG8_MMA(1, 0, At, B0); PG8_MMA(1, 1, At, B1); PG8_BAR; PG8_SCHED;
;             PG8_LDB(B0, 1, 0); PG8_LDB(B1, 1, 1); PG8_SCHED; PG8_LDA(At, 1, 0); PG8_STAGE(PG8_SA(0, 1), a2 + hstepA, voffA);
;             PG8_WAIT_V(8); PG8_WAIT_L(0); PG8_BAR; PG8_MMA(0, 0, At, B0); PG8_MMA(0, 1, At, B1); PG8_BAR; PG8_SCHED;
	s_setprio 1
	v_mfma_f32_16x16x32_bf16 v[62:65], v[164:167], v[214:217], v[62:65]
	v_mfma_f32_16x16x32_bf16 v[58:61], v[186:189], v[214:217], v[58:61]
	v_mfma_f32_16x16x32_bf16 v[54:57], v[164:167], v[222:225], v[54:57]
	v_mfma_f32_16x16x32_bf16 v[50:53], v[186:189], v[222:225], v[50:53]
	v_mfma_f32_16x16x32_bf16 v[38:41], v[164:167], v[230:233], v[38:41]
	v_mfma_f32_16x16x32_bf16 v[34:37], v[186:189], v[230:233], v[34:37]
	v_mfma_f32_16x16x32_bf16 v[22:25], v[164:167], v[238:241], v[22:25]
	v_mfma_f32_16x16x32_bf16 v[18:21], v[186:189], v[238:241], v[18:21]
	v_mfma_f32_16x16x32_bf16 v[62:65], v[168:171], v[218:221], v[62:65]
	v_mfma_f32_16x16x32_bf16 v[58:61], v[190:193], v[218:221], v[58:61]
	v_mfma_f32_16x16x32_bf16 v[54:57], v[168:171], v[226:229], v[54:57]
	v_mfma_f32_16x16x32_bf16 v[50:53], v[190:193], v[226:229], v[50:53]
	v_mfma_f32_16x16x32_bf16 v[38:41], v[168:171], v[234:237], v[38:41]
	v_mfma_f32_16x16x32_bf16 v[34:37], v[190:193], v[234:237], v[34:37]
	v_mfma_f32_16x16x32_bf16 v[22:25], v[168:171], v[242:245], v[22:25]
	v_mfma_f32_16x16x32_bf16 v[18:21], v[190:193], v[242:245], v[18:21]
	s_setprio 0
	s_setprio 1
	v_mfma_f32_16x16x32_bf16 v[46:49], v[198:201], v[214:217], v[46:49]
	v_mfma_f32_16x16x32_bf16 v[42:45], v[206:209], v[214:217], v[42:45]
	v_mfma_f32_16x16x32_bf16 v[30:33], v[198:201], v[222:225], v[30:33]
	v_mfma_f32_16x16x32_bf16 v[26:29], v[206:209], v[222:225], v[26:29]
	v_mfma_f32_16x16x32_bf16 v[14:17], v[198:201], v[230:233], v[14:17]
	v_mfma_f32_16x16x32_bf16 v[10:13], v[206:209], v[230:233], v[10:13]
	v_mfma_f32_16x16x32_bf16 v[6:9], v[198:201], v[238:241], v[6:9]
	v_mfma_f32_16x16x32_bf16 v[2:5], v[206:209], v[238:241], v[2:5]
	v_mfma_f32_16x16x32_bf16 v[46:49], v[202:205], v[218:221], v[46:49]
	v_mfma_f32_16x16x32_bf16 v[42:45], v[210:213], v[218:221], v[42:45]
	v_mfma_f32_16x16x32_bf16 v[30:33], v[202:205], v[226:229], v[30:33]
	v_mfma_f32_16x16x32_bf16 v[26:29], v[210:213], v[226:229], v[26:29]
	v_mfma_f32_16x16x32_bf16 v[14:17], v[202:205], v[234:237], v[14:17]
	v_mfma_f32_16x16x32_bf16 v[10:13], v[210:213], v[234:237], v[10:13]
	v_mfma_f32_16x16x32_bf16 v[6:9], v[202:205], v[242:245], v[6:9]
	v_mfma_f32_16x16x32_bf16 v[2:5], v[210:213], v[242:245], v[2:5]
	s_setprio 0
	s_barrier
	s_add_i32 s69, 0, 0x18000
	v_add_u32_e32 v132, s69, v161
	s_add_i32 s81, 0, 0x1c000
	ds_read_b128 v[164:167], v132
	ds_read_b128 v[168:171], v132 offset:1024
	ds_read_b128 v[186:189], v132 offset:2048
	ds_read_b128 v[190:193], v132 offset:3072
	v_add_u32_e32 v132, s81, v161
	ds_read_b128 v[198:201], v132
	ds_read_b128 v[202:205], v132 offset:1024
	ds_read_b128 v[206:209], v132 offset:2048
	ds_read_b128 v[210:213], v132 offset:3072
	s_add_u32 s10, s50, 0x40000
	s_addc_u32 s11, s51, 0
	s_mov_b32 m0, s31
	v_lshl_add_u64 v[132:133], s[10:11], 0, v[154:155]
	ds_read_b128 v[214:217], v163 offset:32768
	ds_read_b128 v[218:221], v163 offset:33792
	ds_read_b128 v[222:225], v163 offset:34816
	ds_read_b128 v[226:229], v163 offset:35840
	ds_read_b128 v[230:233], v163 offset:36864
	ds_read_b128 v[234:237], v163 offset:37888
	ds_read_b128 v[238:241], v163 offset:38912
	ds_read_b128 v[242:245], v163 offset:39936
	global_load_lds_dwordx4 v[132:133], off
	v_lshl_add_u64 v[132:133], s[10:11], 0, v[152:153]
	s_mov_b32 m0, s34
	s_nop 0
	global_load_lds_dwordx4 v[132:133], off
	s_waitcnt vmcnt(8)
	s_waitcnt lgkmcnt(0)
	s_barrier
	s_setprio 1
	v_mfma_f32_16x16x32_bf16 v[126:129], v[164:167], v[214:217], v[126:129]
	v_mfma_f32_16x16x32_bf16 v[122:125], v[186:189], v[214:217], v[122:125]
	v_mfma_f32_16x16x32_bf16 v[118:121], v[164:167], v[222:225], v[118:121]
	v_mfma_f32_16x16x32_bf16 v[114:117], v[186:189], v[222:225], v[114:117]
	v_mfma_f32_16x16x32_bf16 v[102:105], v[164:167], v[230:233], v[102:105]
	v_mfma_f32_16x16x32_bf16 v[98:101], v[186:189], v[230:233], v[98:101]
	v_mfma_f32_16x16x32_bf16 v[86:89], v[164:167], v[238:241], v[86:89]
	v_mfma_f32_16x16x32_bf16 v[82:85], v[186:189], v[238:241], v[82:85]
	v_mfma_f32_16x16x32_bf16 v[126:129], v[168:171], v[218:221], v[126:129]
	v_mfma_f32_16x16x32_bf16 v[122:125], v[190:193], v[218:221], v[122:125]
	v_mfma_f32_16x16x32_bf16 v[118:121], v[168:171], v[226:229], v[118:121]
	v_mfma_f32_16x16x32_bf16 v[114:117], v[190:193], v[226:229], v[114:117]
	v_mfma_f32_16x16x32_bf16 v[102:105], v[168:171], v[234:237], v[102:105]
	v_mfma_f32_16x16x32_bf16 v[98:101], v[190:193], v[234:237], v[98:101]
	v_mfma_f32_16x16x32_bf16 v[86:89], v[168:171], v[242:245], v[86:89]
	v_mfma_f32_16x16x32_bf16 v[82:85], v[190:193], v[242:245], v[82:85]
	s_setprio 0
	s_setprio 1
	v_mfma_f32_16x16x32_bf16 v[110:113], v[198:201], v[214:217], v[110:113]
	v_mfma_f32_16x16x32_bf16 v[106:109], v[206:209], v[214:217], v[106:109]
	v_mfma_f32_16x16x32_bf16 v[94:97], v[198:201], v[222:225], v[94:97]
	v_mfma_f32_16x16x32_bf16 v[90:93], v[206:209], v[222:225], v[90:93]
	v_mfma_f32_16x16x32_bf16 v[78:81], v[198:201], v[230:233], v[78:81]
	v_mfma_f32_16x16x32_bf16 v[74:77], v[206:209], v[230:233], v[74:77]
	v_mfma_f32_16x16x32_bf16 v[70:73], v[198:201], v[238:241], v[70:73]
	v_mfma_f32_16x16x32_bf16 v[66:69], v[206:209], v[238:241], v[66:69]
	v_mfma_f32_16x16x32_bf16 v[110:113], v[202:205], v[218:221], v[110:113]
	v_mfma_f32_16x16x32_bf16 v[106:109], v[210:213], v[218:221], v[106:109]
	v_mfma_f32_16x16x32_bf16 v[94:97], v[202:205], v[226:229], v[94:97]
	v_mfma_f32_16x16x32_bf16 v[90:93], v[210:213], v[226:229], v[90:93]
	v_mfma_f32_16x16x32_bf16 v[78:81], v[202:205], v[234:237], v[78:81]
	v_mfma_f32_16x16x32_bf16 v[74:77], v[210:213], v[234:237], v[74:77]
	v_mfma_f32_16x16x32_bf16 v[70:73], v[202:205], v[242:245], v[70:73]
	v_mfma_f32_16x16x32_bf16 v[66:69], v[210:213], v[242:245], v[66:69]
	s_setprio 0
	s_barrier
; #define PG8_STAGE(bufoff, gbase, voff) do { _Pragma("unroll") for (int _i = 0; _i < 2; ++_i) \
;         __builtin_amdgcn_global_load_lds((const unsigned*)((const char*)(gbase) + (voff)[_i]), (PG8_LAS unsigned*)(lds + (bufoff) + ldsw + _i * 8192), 16, 0, 0); } while (0)
; #define PG8_LDA(dst, b, h) do { _Pragma("unroll") for (int m = 0; m < 4; ++m) _Pragma("unroll") for (int k = 0; k < 2; ++k) dst[m][k] = *(const PG8_LAS bf16x8*)(lds + PG8_SA(b, h) + aoff + m * 2048 + k * 1024); } while (0)
; #define PG8_MMA(ai, bj, At, Bt) do { __builtin_amdgcn_s_setprio(1); _Pragma("unroll") for (int m = 0; m < 4; ++m) _Pragma("unroll") for (int n = 0; n < 2; ++n) _Pragma("unroll") for (int k = 0; k < 2; ++k) \
;         acc[ai][bj][m][n] = __builtin_amdgcn_mfma_f32_16x16x32_bf16(Bt[n][k], At[m][k], acc[ai][bj][m][n], 0, 0, 0); __builtin_amdgcn_s_setprio(0); } while (0)
; #define PG8_WAIT_V(n) asm volatile("s_waitcnt vmcnt(" #n ")" ::: "memory")
; #define PG8_WAIT_L(n) asm volatile("s_waitcnt lgkmcnt(" #n ")" ::: "memory")
; #define PG8_BAR __builtin_amdgcn_s_barrier()
; #define PG8_SCHED __builtin_amdgcn_sched_barrier(0)
; template <class Epi, class Sched, bool ALIGN_EPI = false, bool SP2 = false>
; __device__ __forceinline__ void gemm_phase(PG8_LAS unsigned char* lds, const Gemm g, const Sched& S, const Epi& E) {
;     ...
;             const bool last = (t == nt - 2);
;             const char* a1 = cA + (size_t)(t + 1) * kstep;
;             const char* a2 = last ? nA : cA + (size_t)(t + 2) * kstep; const char* b2 = last ? nB : cB + (size_t)(t + 2) * kstep;
;             const char* a3 = a2 + kstep; const char* b3 = b2 + kstep;
;     ...
;             PG8_LDA(At, 1, 1); PG8_STAGE(PG8_SB(1, 0), b3, voffB); PG8_STAGE(PG8_SB(1, 1), b3 + hstepB, voffB); PG8_STAGE(PG8_SA(1, 0), a3, voffA);
;             PG8_WAIT_V(8); PG8_WAIT_L(0); PG8_BAR; PG8_MMA(1, 0, At, B0); PG8_MMA(1, 1, At, B1); PG8_BAR; PG8_SCHED;
	s_add_i32 s10, s69, s8
	v_lshl_add_u64 v[132:133], v[172:173], 0, s[2:3]
	s_mov_b32 m0, s10
	ds_read_b128 v[214:217], v163 offset:49152
	ds_read_b128 v[218:221], v163 offset:50176
	ds_read_b128 v[222:225], v163 offset:51200
	ds_read_b128 v[226:229], v163 offset:52224
	ds_read_b128 v[230:233], v163 offset:53248
	ds_read_b128 v[234:237], v163 offset:54272
	ds_read_b128 v[238:241], v163 offset:55296
	ds_read_b128 v[242:245], v163 offset:56320
	global_load_lds_dwordx4 v[132:133], off
	s_add_i32 m0, s10, 0x2000
	s_add_u32 s10, s48, 0x40080
	v_lshl_add_u64 v[132:133], v[246:247], 0, s[2:3]
	s_addc_u32 s11, s49, 0
	s_add_i32 s48, s81, s8
	global_load_lds_dwordx4 v[132:133], off
	v_lshl_add_u64 v[132:133], s[10:11], 0, v[0:1]
	s_mov_b32 m0, s48
	v_lshl_add_u64 v[130:131], v[130:131], 0, s[2:3]
	global_load_lds_dwordx4 v[132:133], off
	v_lshl_add_u64 v[132:133], s[10:11], 0, v[150:151]
	s_add_i32 m0, s48, 0x2000
	s_nop 0
	global_load_lds_dwordx4 v[132:133], off
	v_lshl_add_u64 v[132:133], v[248:249], 0, s[2:3]
	s_mov_b32 m0, s35
	s_nop 0
	global_load_lds_dwordx4 v[132:133], off
	s_mov_b32 m0, s52
	s_nop 0
	global_load_lds_dwordx4 v[130:131], off
	s_waitcnt vmcnt(8)
	s_waitcnt lgkmcnt(0)
	s_barrier
	s_setprio 1
	v_mfma_f32_16x16x32_bf16 v[62:65], v[164:167], v[214:217], v[62:65]
	v_mfma_f32_16x16x32_bf16 v[58:61], v[186:189], v[214:217], v[58:61]
	s_add_i32 s68, s68, 2
	v_mfma_f32_16x16x32_bf16 v[54:57], v[164:167], v[222:225], v[54:57]
	s_add_u32 s46, s46, 0x100
	v_mfma_f32_16x16x32_bf16 v[50:53], v[186:189], v[222:225], v[50:53]
	s_addc_u32 s47, s47, 0
	v_mfma_f32_16x16x32_bf16 v[38:41], v[164:167], v[230:233], v[38:41]
	s_add_u32 s62, s62, 0x100
	v_mfma_f32_16x16x32_bf16 v[34:37], v[186:189], v[230:233], v[34:37]
	s_addc_u32 s63, s63, 0
	v_mfma_f32_16x16x32_bf16 v[22:25], v[164:167], v[238:241], v[22:25]
	s_add_u32 s10, s46, 0xfffc0080
	v_mfma_f32_16x16x32_bf16 v[18:21], v[186:189], v[238:241], v[18:21]
	s_addc_u32 s11, s47, -1
	v_mfma_f32_16x16x32_bf16 v[62:65], v[168:171], v[218:221], v[62:65]
	s_add_i32 s69, 0, 0x10000
	v_mfma_f32_16x16x32_bf16 v[58:61], v[190:193], v[218:221], v[58:61]
	s_cmp_eq_u32 s68, 12
	v_mfma_f32_16x16x32_bf16 v[54:57], v[168:171], v[226:229], v[54:57]
	s_cselect_b32 s51, s41, s11
	v_mfma_f32_16x16x32_bf16 v[50:53], v[190:193], v[226:229], v[50:53]
	s_cselect_b32 s50, s57, s10
	v_mfma_f32_16x16x32_bf16 v[38:41], v[168:171], v[234:237], v[38:41]
	v_add_u32_e32 v130, s69, v161
	v_mfma_f32_16x16x32_bf16 v[34:37], v[190:193], v[234:237], v[34:37]
	s_cselect_b32 s49, s4, s63
	v_mfma_f32_16x16x32_bf16 v[22:25], v[168:171], v[242:245], v[22:25]
	s_cselect_b32 s48, s39, s62
	v_mfma_f32_16x16x32_bf16 v[18:21], v[190:193], v[242:245], v[18:21]
	s_add_i32 s81, 0, 0x14000
	s_setprio 0
	s_setprio 1
	v_mfma_f32_16x16x32_bf16 v[46:49], v[198:201], v[214:217], v[46:49]
	s_cmp_gt_u32 s68, 13
	v_mfma_f32_16x16x32_bf16 v[42:45], v[206:209], v[214:217], v[42:45]
	v_mfma_f32_16x16x32_bf16 v[30:33], v[198:201], v[222:225], v[30:33]
	v_mfma_f32_16x16x32_bf16 v[26:29], v[206:209], v[222:225], v[26:29]
	v_mfma_f32_16x16x32_bf16 v[14:17], v[198:201], v[230:233], v[14:17]
	v_mfma_f32_16x16x32_bf16 v[10:13], v[206:209], v[230:233], v[10:13]
	v_mfma_f32_16x16x32_bf16 v[6:9], v[198:201], v[238:241], v[6:9]
	v_mfma_f32_16x16x32_bf16 v[2:5], v[206:209], v[238:241], v[2:5]
	v_mfma_f32_16x16x32_bf16 v[46:49], v[202:205], v[218:221], v[46:49]
	v_mfma_f32_16x16x32_bf16 v[42:45], v[210:213], v[218:221], v[42:45]
	v_mfma_f32_16x16x32_bf16 v[30:33], v[202:205], v[226:229], v[30:33]
	v_mfma_f32_16x16x32_bf16 v[26:29], v[210:213], v[226:229], v[26:29]
	v_mfma_f32_16x16x32_bf16 v[14:17], v[202:205], v[234:237], v[14:17]
	v_mfma_f32_16x16x32_bf16 v[10:13], v[210:213], v[234:237], v[10:13]
	v_mfma_f32_16x16x32_bf16 v[6:9], v[202:205], v[242:245], v[6:9]
	v_mfma_f32_16x16x32_bf16 v[2:5], v[210:213], v[242:245], v[2:5]
	s_setprio 0
	s_barrier
	s_cbranch_scc0 .Lgk_146
	s_and_b64 vcc, exec, s[20:21]
	s_cbranch_vccz .LBB0_149
	s_barrier

; #define PG8_STAGE(bufoff, gbase, voff) do { _Pragma("unroll") for (int _i = 0; _i < 2; ++_i) \
;         __builtin_amdgcn_global_load_lds((const unsigned*)((const char*)(gbase) + (voff)[_i]), (PG8_LAS unsigned*)(lds + (bufoff) + ldsw + _i * 8192), 16, 0, 0); } while (0)
; #define PG8_LDA(dst, b, h) do { _Pragma("unroll") for (int m = 0; m < 4; ++m) _Pragma("unroll") for (int k = 0; k < 2; ++k) dst[m][k] = *(const PG8_LAS bf16x8*)(lds + PG8_SA(b, h) + aoff + m * 2048 + k * 1024); } while (0)
; #define PG8_LDB(dst, b, h) do { _Pragma("unroll") for (int n = 0; n < 2; ++n) _Pragma("unroll") for (int k = 0; k < 2; ++k) dst[n][k] = *(const PG8_LAS bf16x8*)(lds + PG8_SB(b, h) + boff + n * 2048 + k * 1024); } while (0)
; #define PG8_MMA(ai, bj, At, Bt) do { __builtin_amdgcn_s_setprio(1); _Pragma("unroll") for (int m = 0; m < 4; ++m) _Pragma("unroll") for (int n = 0; n < 2; ++n) _Pragma("unroll") for (int k = 0; k < 2; ++k) \
;         acc[ai][bj][m][n] = __builtin_amdgcn_mfma_f32_16x16x32_bf16(Bt[n][k], At[m][k], acc[ai][bj][m][n], 0, 0, 0); __builtin_amdgcn_s_setprio(0); } while (0)
; #define PG8_WAIT_V(n) asm volatile("s_waitcnt vmcnt(" #n ")" ::: "memory")
; #define PG8_WAIT_L(n) asm volatile("s_waitcnt lgkmcnt(" #n ")" ::: "memory")
; #define PG8_BAR __builtin_amdgcn_s_barrier()
; #define PG8_SCHED __builtin_amdgcn_sched_barrier(0)
; template <class Epi, class Sched, bool ALIGN_EPI = false, bool SP2 = false>
; __device__ __forceinline__ void gemm_phase(PG8_LAS unsigned char* lds, const Gemm g, const Sched& S, const Epi& E) {
;     ...
;             PG8_LDB(B0, 0, 0); PG8_LDB(B1, 0, 1); PG8_SCHED; PG8_LDA(At, 0, 0); PG8_STAGE(PG8_SA(1, 1), a1 + hstepA, voffA);
;             PG8_WAIT_V(8); PG8_WAIT_L(0); PG8_BAR; PG8_MMA(0, 0, At, B0); PG8_MMA(0, 1, At, B1); PG8_BAR; PG8_SCHED;
;             PG8_LDA(At, 0, 1); PG8_STAGE(PG8_SB(0, 0), b2, voffB); PG8_STAGE(PG8_SB(0, 1), b2 + hstepB, voffB); PG8_STAGE(PG8_SA(0, 0), a2, voffA);
.Lgk_603:
	ds_read_b128 v[166:169], v130
	ds_read_b128 v[170:173], v130 offset:1024
	ds_read_b128 v[186:189], v130 offset:2048
	ds_read_b128 v[190:193], v130 offset:3072
	v_add_u32_e32 v130, s13, v163
	ds_read_b128 v[198:201], v130
	ds_read_b128 v[202:205], v130 offset:1024
	ds_read_b128 v[206:209], v130 offset:2048
	ds_read_b128 v[210:213], v130 offset:3072
	v_lshl_add_u64 v[130:131], s[50:51], 0, v[156:157]
	s_add_i32 m0, s31, 0xc000
	ds_read_b128 v[214:217], v165
	ds_read_b128 v[218:221], v165 offset:1024
	ds_read_b128 v[222:225], v165 offset:2048
	ds_read_b128 v[226:229], v165 offset:3072
	ds_read_b128 v[230:233], v165 offset:4096
	ds_read_b128 v[234:237], v165 offset:5120
	ds_read_b128 v[238:241], v165 offset:6144
	ds_read_b128 v[242:245], v165 offset:7168
	global_load_lds_dwordx4 v[130:131], off
	v_lshl_add_u64 v[130:131], s[50:51], 0, v[158:159]
	s_add_i32 m0, s31, 0xe000
	s_nop 0
	global_load_lds_dwordx4 v[130:131], off
	s_waitcnt vmcnt(8)
	s_waitcnt lgkmcnt(0)
	s_barrier
	s_setprio 1
	v_mfma_f32_16x16x32_bf16 v[126:129], v[166:169], v[214:217], v[126:129]
	v_mfma_f32_16x16x32_bf16 v[122:125], v[186:189], v[214:217], v[122:125]
	v_mfma_f32_16x16x32_bf16 v[110:113], v[166:169], v[222:225], v[110:113]
	v_mfma_f32_16x16x32_bf16 v[106:109], v[186:189], v[222:225], v[106:109]
	v_mfma_f32_16x16x32_bf16 v[94:97], v[166:169], v[230:233], v[94:97]
	v_mfma_f32_16x16x32_bf16 v[90:93], v[186:189], v[230:233], v[90:93]
	v_mfma_f32_16x16x32_bf16 v[78:81], v[166:169], v[238:241], v[78:81]
	v_mfma_f32_16x16x32_bf16 v[74:77], v[186:189], v[238:241], v[74:77]
	v_mfma_f32_16x16x32_bf16 v[126:129], v[170:173], v[218:221], v[126:129]
	v_mfma_f32_16x16x32_bf16 v[122:125], v[190:193], v[218:221], v[122:125]
	v_mfma_f32_16x16x32_bf16 v[110:113], v[170:173], v[226:229], v[110:113]
	v_mfma_f32_16x16x32_bf16 v[106:109], v[190:193], v[226:229], v[106:109]
	v_mfma_f32_16x16x32_bf16 v[94:97], v[170:173], v[234:237], v[94:97]
	v_mfma_f32_16x16x32_bf16 v[90:93], v[190:193], v[234:237], v[90:93]
	v_mfma_f32_16x16x32_bf16 v[78:81], v[170:173], v[242:245], v[78:81]
	v_mfma_f32_16x16x32_bf16 v[74:77], v[190:193], v[242:245], v[74:77]
	s_setprio 0
	s_setprio 1
	v_mfma_f32_16x16x32_bf16 v[118:121], v[198:201], v[214:217], v[118:121]
	v_mfma_f32_16x16x32_bf16 v[114:117], v[206:209], v[214:217], v[114:117]
	v_mfma_f32_16x16x32_bf16 v[102:105], v[198:201], v[222:225], v[102:105]
	v_mfma_f32_16x16x32_bf16 v[98:101], v[206:209], v[222:225], v[98:101]
	v_mfma_f32_16x16x32_bf16 v[86:89], v[198:201], v[230:233], v[86:89]
	v_mfma_f32_16x16x32_bf16 v[82:85], v[206:209], v[230:233], v[82:85]
	v_mfma_f32_16x16x32_bf16 v[70:73], v[198:201], v[238:241], v[70:73]
	v_mfma_f32_16x16x32_bf16 v[66:69], v[206:209], v[238:241], v[66:69]
	v_mfma_f32_16x16x32_bf16 v[118:121], v[202:205], v[218:221], v[118:121]
	v_mfma_f32_16x16x32_bf16 v[114:117], v[210:213], v[218:221], v[114:117]
	v_mfma_f32_16x16x32_bf16 v[102:105], v[202:205], v[226:229], v[102:105]
	v_mfma_f32_16x16x32_bf16 v[98:101], v[210:213], v[226:229], v[98:101]
	v_mfma_f32_16x16x32_bf16 v[86:89], v[202:205], v[234:237], v[86:89]
	v_mfma_f32_16x16x32_bf16 v[82:85], v[210:213], v[234:237], v[82:85]
	v_mfma_f32_16x16x32_bf16 v[70:73], v[202:205], v[242:245], v[70:73]
	v_mfma_f32_16x16x32_bf16 v[66:69], v[210:213], v[242:245], v[66:69]
	s_setprio 0
	s_barrier
	s_add_i32 s10, s12, s30
	v_lshl_add_u64 v[130:131], s[52:53], 0, v[0:1]
	s_mov_b32 m0, s10
	ds_read_b128 v[214:217], v165 offset:16384
	ds_read_b128 v[218:221], v165 offset:17408
	ds_read_b128 v[222:225], v165 offset:18432
	ds_read_b128 v[226:229], v165 offset:19456
	ds_read_b128 v[230:233], v165 offset:20480
	ds_read_b128 v[234:237], v165 offset:21504
	ds_read_b128 v[238:241], v165 offset:22528
	ds_read_b128 v[242:245], v165 offset:23552
	global_load_lds_dwordx4 v[130:131], off
	s_add_i32 m0, s10, 0x2000
	s_add_u32 s10, s52, 0x40000
	v_lshl_add_u64 v[132:133], s[52:53], 0, v[150:151]
	s_addc_u32 s11, s53, 0
	s_add_i32 s12, s13, s30
	global_load_lds_dwordx4 v[132:133], off
	v_lshl_add_u64 v[160:161], s[10:11], 0, v[0:1]
	s_mov_b32 m0, s12
	v_lshl_add_u64 v[246:247], s[54:55], 0, v[152:153]
	global_load_lds_dwordx4 v[160:161], off
	v_lshl_add_u64 v[160:161], s[10:11], 0, v[150:151]
	s_add_i32 m0, s12, 0x2000
	s_nop 0
	global_load_lds_dwordx4 v[160:161], off
	v_lshl_add_u64 v[160:161], s[54:55], 0, v[154:155]
	s_mov_b32 m0, s31
	s_nop 0
	global_load_lds_dwordx4 v[160:161], off
	s_mov_b32 m0, s34
	s_nop 0
	global_load_lds_dwordx4 v[246:247], off
	s_waitcnt vmcnt(8)
	s_waitcnt lgkmcnt(0)
	s_barrier
; #define PG8_STAGE(bufoff, gbase, voff) do { _Pragma("unroll") for (int _i = 0; _i < 2; ++_i) \
;         __builtin_amdgcn_global_load_lds((const unsigned*)((const char*)(gbase) + (voff)[_i]), (PG8_LAS unsigned*)(lds + (bufoff) + ldsw + _i * 8192), 16, 0, 0); } while (0)
; #define PG8_LDA(dst, b, h) do { _Pragma("unroll") for (int m = 0; m < 4; ++m) _Pragma("unroll") for (int k = 0; k < 2; ++k) dst[m][k] = *(const PG8_LAS bf16x8*)(lds + PG8_SA(b, h) + aoff + m * 2048 + k * 1024); } while (0)
; #define PG8_LDB(dst, b, h) do { _Pragma("unroll") for (int n = 0; n < 2; ++n) _Pragma("unroll") for (int k = 0; k < 2; ++k) dst[n][k] = *(const PG8_LAS bf16x8*)(lds + PG8_SB(b, h) + boff + n * 2048 + k * 1024); } while (0)
; #define PG8_MMA(ai, bj, At, Bt) do { __builtin_amdgcn_s_setprio(1); _Pragma("unroll") for (int m = 0; m < 4; ++m) _Pragma("unroll") for (int n = 0; n < 2; ++n) _Pragma("unroll") for (int k = 0; k < 2; ++k) \
;         acc[ai][bj][m][n] = __builtin_amdgcn_mfma_f32_16x16x32_bf16(Bt[n][k], At[m][k], acc[ai][bj][m][n], 0, 0, 0); __builtin_amdgcn_s_setprio(0); } while (0)
; #define PG8_WAIT_V(n) asm volatile("s_waitcnt vmcnt(" #n ")" ::: "memory")
; #define PG8_WAIT_L(n) asm volatile("s_waitcnt lgkmcnt(" #n ")" ::: "memory")
; #define PG8_BAR __builtin_amdgcn_s_barrier()
; #define PG8_SCHED __builtin_amdgcn_sched_barrier(0)
; template <class Epi, class Sched, bool ALIGN_EPI = false, bool SP2 = false>
; __device__ __forceinline__ void gemm_phase(PG8_LAS unsigned char* lds, const Gemm g, const Sched& S, const Epi& E) {
;     ...
;             PG8_WAIT_V(8); PG8_WAIT_L(0); PG8_BAR; PG8_MMA(1, 0, At, B0); PG8_MMA(1, 1, At, B1); PG8_BAR; PG8_SCHED;
;             PG8_LDB(B0, 1, 0); PG8_LDB(B1, 1, 1); PG8_SCHED; PG8_LDA(At, 1, 0); PG8_STAGE(PG8_SA(0, 1), a2 + hstepA, voffA);
;             PG8_WAIT_V(8); PG8_WAIT_L(0); PG8_BAR; PG8_MMA(0, 0, At, B0); PG8_MMA(0, 1, At, B1); PG8_BAR; PG8_SCHED;
	s_setprio 1
	v_mfma_f32_16x16x32_bf16 v[62:65], v[166:169], v[214:217], v[62:65]
	v_mfma_f32_16x16x32_bf16 v[58:61], v[186:189], v[214:217], v[58:61]
	v_mfma_f32_16x16x32_bf16 v[46:49], v[166:169], v[222:225], v[46:49]
	v_mfma_f32_16x16x32_bf16 v[42:45], v[186:189], v[222:225], v[42:45]
	v_mfma_f32_16x16x32_bf16 v[30:33], v[166:169], v[230:233], v[30:33]
	v_mfma_f32_16x16x32_bf16 v[26:29], v[186:189], v[230:233], v[26:29]
	v_mfma_f32_16x16x32_bf16 v[14:17], v[166:169], v[238:241], v[14:17]
	v_mfma_f32_16x16x32_bf16 v[10:13], v[186:189], v[238:241], v[10:13]
	v_mfma_f32_16x16x32_bf16 v[62:65], v[170:173], v[218:221], v[62:65]
	v_mfma_f32_16x16x32_bf16 v[58:61], v[190:193], v[218:221], v[58:61]
	v_mfma_f32_16x16x32_bf16 v[46:49], v[170:173], v[226:229], v[46:49]
	v_mfma_f32_16x16x32_bf16 v[42:45], v[190:193], v[226:229], v[42:45]
	v_mfma_f32_16x16x32_bf16 v[30:33], v[170:173], v[234:237], v[30:33]
	v_mfma_f32_16x16x32_bf16 v[26:29], v[190:193], v[234:237], v[26:29]
	v_mfma_f32_16x16x32_bf16 v[14:17], v[170:173], v[242:245], v[14:17]
	v_mfma_f32_16x16x32_bf16 v[10:13], v[190:193], v[242:245], v[10:13]
	s_setprio 0
	s_setprio 1
	v_mfma_f32_16x16x32_bf16 v[54:57], v[198:201], v[214:217], v[54:57]
	v_mfma_f32_16x16x32_bf16 v[50:53], v[206:209], v[214:217], v[50:53]
	v_mfma_f32_16x16x32_bf16 v[38:41], v[198:201], v[222:225], v[38:41]
	v_mfma_f32_16x16x32_bf16 v[34:37], v[206:209], v[222:225], v[34:37]
	v_mfma_f32_16x16x32_bf16 v[22:25], v[198:201], v[230:233], v[22:25]
	v_mfma_f32_16x16x32_bf16 v[18:21], v[206:209], v[230:233], v[18:21]
	v_mfma_f32_16x16x32_bf16 v[6:9], v[198:201], v[238:241], v[6:9]
	v_mfma_f32_16x16x32_bf16 v[2:5], v[206:209], v[238:241], v[2:5]
	v_mfma_f32_16x16x32_bf16 v[54:57], v[202:205], v[218:221], v[54:57]
	v_mfma_f32_16x16x32_bf16 v[50:53], v[210:213], v[218:221], v[50:53]
	v_mfma_f32_16x16x32_bf16 v[38:41], v[202:205], v[226:229], v[38:41]
	v_mfma_f32_16x16x32_bf16 v[34:37], v[210:213], v[226:229], v[34:37]
	v_mfma_f32_16x16x32_bf16 v[22:25], v[202:205], v[234:237], v[22:25]
	v_mfma_f32_16x16x32_bf16 v[18:21], v[210:213], v[234:237], v[18:21]
	v_mfma_f32_16x16x32_bf16 v[6:9], v[202:205], v[242:245], v[6:9]
	v_mfma_f32_16x16x32_bf16 v[2:5], v[210:213], v[242:245], v[2:5]
	s_setprio 0
	s_barrier
	s_add_i32 s12, 0, 0x18000
	s_add_i32 s13, 0, 0x1c000
	v_add_u32_e32 v190, s12, v163
	v_add_u32_e32 v210, s13, v163
	ds_read_b128 v[166:169], v190
	ds_read_b128 v[170:173], v190 offset:1024
	ds_read_b128 v[186:189], v190 offset:2048
	ds_read_b128 v[190:193], v190 offset:3072
	ds_read_b128 v[198:201], v210
	ds_read_b128 v[202:205], v210 offset:1024
	ds_read_b128 v[206:209], v210 offset:2048
	ds_read_b128 v[210:213], v210 offset:3072
	s_add_u32 s10, s54, 0x40000
	s_addc_u32 s11, s55, 0
	s_mov_b32 m0, s35
	v_lshl_add_u64 v[248:249], s[10:11], 0, v[154:155]
	ds_read_b128 v[214:217], v165 offset:32768
	ds_read_b128 v[218:221], v165 offset:33792
	ds_read_b128 v[222:225], v165 offset:34816
	ds_read_b128 v[226:229], v165 offset:35840
	ds_read_b128 v[230:233], v165 offset:36864
	ds_read_b128 v[234:237], v165 offset:37888
	ds_read_b128 v[238:241], v165 offset:38912
	ds_read_b128 v[242:245], v165 offset:39936
	global_load_lds_dwordx4 v[248:249], off
	v_lshl_add_u64 v[248:249], s[10:11], 0, v[152:153]
	s_mov_b32 m0, s56
	s_nop 0
	global_load_lds_dwordx4 v[248:249], off
	s_waitcnt vmcnt(8)
	s_waitcnt lgkmcnt(0)
	s_barrier
	s_setprio 1
	v_mfma_f32_16x16x32_bf16 v[126:129], v[166:169], v[214:217], v[126:129]
	v_mfma_f32_16x16x32_bf16 v[122:125], v[186:189], v[214:217], v[122:125]
	v_mfma_f32_16x16x32_bf16 v[110:113], v[166:169], v[222:225], v[110:113]
	v_mfma_f32_16x16x32_bf16 v[106:109], v[186:189], v[222:225], v[106:109]
	v_mfma_f32_16x16x32_bf16 v[94:97], v[166:169], v[230:233], v[94:97]
	v_mfma_f32_16x16x32_bf16 v[90:93], v[186:189], v[230:233], v[90:93]
	v_mfma_f32_16x16x32_bf16 v[78:81], v[166:169], v[238:241], v[78:81]
	v_mfma_f32_16x16x32_bf16 v[74:77], v[186:189], v[238:241], v[74:77]
	v_mfma_f32_16x16x32_bf16 v[126:129], v[170:173], v[218:221], v[126:129]
	v_mfma_f32_16x16x32_bf16 v[122:125], v[190:193], v[218:221], v[122:125]
	v_mfma_f32_16x16x32_bf16 v[110:113], v[170:173], v[226:229], v[110:113]
	v_mfma_f32_16x16x32_bf16 v[106:109], v[190:193], v[226:229], v[106:109]
	v_mfma_f32_16x16x32_bf16 v[94:97], v[170:173], v[234:237], v[94:97]
	v_mfma_f32_16x16x32_bf16 v[90:93], v[190:193], v[234:237], v[90:93]
	v_mfma_f32_16x16x32_bf16 v[78:81], v[170:173], v[242:245], v[78:81]
	v_mfma_f32_16x16x32_bf16 v[74:77], v[190:193], v[242:245], v[74:77]
	s_setprio 0
	s_setprio 1
	v_mfma_f32_16x16x32_bf16 v[118:121], v[198:201], v[214:217], v[118:121]
	v_mfma_f32_16x16x32_bf16 v[114:117], v[206:209], v[214:217], v[114:117]
	v_mfma_f32_16x16x32_bf16 v[102:105], v[198:201], v[222:225], v[102:105]
	v_mfma_f32_16x16x32_bf16 v[98:101], v[206:209], v[222:225], v[98:101]
	v_mfma_f32_16x16x32_bf16 v[86:89], v[198:201], v[230:233], v[86:89]
	v_mfma_f32_16x16x32_bf16 v[82:85], v[206:209], v[230:233], v[82:85]
	v_mfma_f32_16x16x32_bf16 v[70:73], v[198:201], v[238:241], v[70:73]
	v_mfma_f32_16x16x32_bf16 v[66:69], v[206:209], v[238:241], v[66:69]
	v_mfma_f32_16x16x32_bf16 v[118:121], v[202:205], v[218:221], v[118:121]
	v_mfma_f32_16x16x32_bf16 v[114:117], v[210:213], v[218:221], v[114:117]
	v_mfma_f32_16x16x32_bf16 v[102:105], v[202:205], v[226:229], v[102:105]
	v_mfma_f32_16x16x32_bf16 v[98:101], v[210:213], v[226:229], v[98:101]
	v_mfma_f32_16x16x32_bf16 v[86:89], v[202:205], v[234:237], v[86:89]
	v_mfma_f32_16x16x32_bf16 v[82:85], v[210:213], v[234:237], v[82:85]
	v_mfma_f32_16x16x32_bf16 v[70:73], v[202:205], v[242:245], v[70:73]
	v_mfma_f32_16x16x32_bf16 v[66:69], v[210:213], v[242:245], v[66:69]
	s_setprio 0
	s_barrier
; #define PG8_STAGE(bufoff, gbase, voff) do { _Pragma("unroll") for (int _i = 0; _i < 2; ++_i) \
;         __builtin_amdgcn_global_load_lds((const unsigned*)((const char*)(gbase) + (voff)[_i]), (PG8_LAS unsigned*)(lds + (bufoff) + ldsw + _i * 8192), 16, 0, 0); } while (0)
; #define PG8_LDA(dst, b, h) do { _Pragma("unroll") for (int m = 0; m < 4; ++m) _Pragma("unroll") for (int k = 0; k < 2; ++k) dst[m][k] = *(const PG8_LAS bf16x8*)(lds + PG8_SA(b, h) + aoff + m * 2048 + k * 1024); } while (0)
; #define PG8_MMA(ai, bj, At, Bt) do { __builtin_amdgcn_s_setprio(1); _Pragma("unroll") for (int m = 0; m < 4; ++m) _Pragma("unroll") for (int n = 0; n < 2; ++n) _Pragma("unroll") for (int k = 0; k < 2; ++k) \
;         acc[ai][bj][m][n] = __builtin_amdgcn_mfma_f32_16x16x32_bf16(Bt[n][k], At[m][k], acc[ai][bj][m][n], 0, 0, 0); __builtin_amdgcn_s_setprio(0); } while (0)
; #define PG8_WAIT_V(n) asm volatile("s_waitcnt vmcnt(" #n ")" ::: "memory")
; #define PG8_WAIT_L(n) asm volatile("s_waitcnt lgkmcnt(" #n ")" ::: "memory")
; #define PG8_BAR __builtin_amdgcn_s_barrier()
; #define PG8_SCHED __builtin_amdgcn_sched_barrier(0)
; template <class Epi, class Sched, bool ALIGN_EPI = false, bool SP2 = false>
; __device__ __forceinline__ void gemm_phase(PG8_LAS unsigned char* lds, const Gemm g, const Sched& S, const Epi& E) {
;     ...
;             const bool last = (t == nt - 2);
;             const char* a1 = cA + (size_t)(t + 1) * kstep;
;             const char* a2 = last ? nA : cA + (size_t)(t + 2) * kstep; const char* b2 = last ? nB : cB + (size_t)(t + 2) * kstep;
;             const char* a3 = a2 + kstep; const char* b3 = b2 + kstep;
;     ...
;             PG8_LDA(At, 1, 1); PG8_STAGE(PG8_SB(1, 0), b3, voffB); PG8_STAGE(PG8_SB(1, 1), b3 + hstepB, voffB); PG8_STAGE(PG8_SA(1, 0), a3, voffA);
;             PG8_WAIT_V(8); PG8_WAIT_L(0); PG8_BAR; PG8_MMA(1, 0, At, B0); PG8_MMA(1, 1, At, B1); PG8_BAR; PG8_SCHED;
	s_add_i32 s10, s12, s30
	v_lshl_add_u64 v[130:131], v[130:131], 0, s[2:3]
	s_mov_b32 m0, s10
	ds_read_b128 v[214:217], v165 offset:49152
	ds_read_b128 v[218:221], v165 offset:50176
	ds_read_b128 v[222:225], v165 offset:51200
	ds_read_b128 v[226:229], v165 offset:52224
	ds_read_b128 v[230:233], v165 offset:53248
	ds_read_b128 v[234:237], v165 offset:54272
	ds_read_b128 v[238:241], v165 offset:55296
	ds_read_b128 v[242:245], v165 offset:56320
	global_load_lds_dwordx4 v[130:131], off
	s_add_i32 m0, s10, 0x2000
	s_add_u32 s10, s52, 0x40080
	v_lshl_add_u64 v[130:131], v[132:133], 0, s[2:3]
	s_addc_u32 s11, s53, 0
	s_add_i32 s12, s13, s30
	global_load_lds_dwordx4 v[130:131], off
	v_lshl_add_u64 v[130:131], s[10:11], 0, v[0:1]
	s_mov_b32 m0, s12
	s_nop 0
	global_load_lds_dwordx4 v[130:131], off
	v_lshl_add_u64 v[130:131], s[10:11], 0, v[150:151]
	s_add_i32 m0, s12, 0x2000
	s_nop 0
	global_load_lds_dwordx4 v[130:131], off
	v_lshl_add_u64 v[130:131], v[160:161], 0, s[2:3]
	s_mov_b32 m0, s57
	s_nop 0
	global_load_lds_dwordx4 v[130:131], off
	v_lshl_add_u64 v[130:131], v[246:247], 0, s[2:3]
	s_mov_b32 m0, s62
	s_nop 0
	global_load_lds_dwordx4 v[130:131], off
	s_waitcnt vmcnt(8)
	s_waitcnt lgkmcnt(0)
	s_barrier
	s_setprio 1
	v_mfma_f32_16x16x32_bf16 v[62:65], v[166:169], v[214:217], v[62:65]
	v_mfma_f32_16x16x32_bf16 v[58:61], v[186:189], v[214:217], v[58:61]
	s_add_i32 s95, s95, 2
	v_mfma_f32_16x16x32_bf16 v[46:49], v[166:169], v[222:225], v[46:49]
	s_add_u32 s50, s50, 0x100
	v_mfma_f32_16x16x32_bf16 v[42:45], v[186:189], v[222:225], v[42:45]
	s_addc_u32 s51, s51, 0
	v_mfma_f32_16x16x32_bf16 v[30:33], v[166:169], v[230:233], v[30:33]
	s_add_u32 s91, s91, 0x100
	v_mfma_f32_16x16x32_bf16 v[26:29], v[186:189], v[230:233], v[26:29]
	s_addc_u32 s94, s94, 0
	v_mfma_f32_16x16x32_bf16 v[14:17], v[166:169], v[238:241], v[14:17]
	s_add_u32 s10, s50, 0xfffc0080
	v_mfma_f32_16x16x32_bf16 v[10:13], v[186:189], v[238:241], v[10:13]
	s_addc_u32 s11, s51, -1
	v_mfma_f32_16x16x32_bf16 v[62:65], v[170:173], v[218:221], v[62:65]
	s_add_i32 s12, 0, 0x10000
	v_mfma_f32_16x16x32_bf16 v[58:61], v[190:193], v[218:221], v[58:61]
	s_cmp_eq_u32 s95, 12
	v_mfma_f32_16x16x32_bf16 v[46:49], v[170:173], v[226:229], v[46:49]
	s_cselect_b32 s55, s45, s11
	v_mfma_f32_16x16x32_bf16 v[42:45], v[190:193], v[226:229], v[42:45]
	s_cselect_b32 s54, s90, s10
	v_mfma_f32_16x16x32_bf16 v[30:33], v[170:173], v[234:237], v[30:33]
	v_add_u32_e32 v130, s12, v163
	v_mfma_f32_16x16x32_bf16 v[26:29], v[190:193], v[234:237], v[26:29]
	s_cselect_b32 s53, s4, s94
	v_mfma_f32_16x16x32_bf16 v[14:17], v[170:173], v[242:245], v[14:17]
	s_cselect_b32 s52, s43, s91
	v_mfma_f32_16x16x32_bf16 v[10:13], v[190:193], v[242:245], v[10:13]
	s_add_i32 s13, 0, 0x14000
	s_setprio 0
	s_setprio 1
	v_mfma_f32_16x16x32_bf16 v[54:57], v[198:201], v[214:217], v[54:57]
	s_cmp_gt_u32 s95, 13
	v_mfma_f32_16x16x32_bf16 v[50:53], v[206:209], v[214:217], v[50:53]
	v_mfma_f32_16x16x32_bf16 v[38:41], v[198:201], v[222:225], v[38:41]
	v_mfma_f32_16x16x32_bf16 v[34:37], v[206:209], v[222:225], v[34:37]
	v_mfma_f32_16x16x32_bf16 v[22:25], v[198:201], v[230:233], v[22:25]
	v_mfma_f32_16x16x32_bf16 v[18:21], v[206:209], v[230:233], v[18:21]
	v_mfma_f32_16x16x32_bf16 v[6:9], v[198:201], v[238:241], v[6:9]
	v_mfma_f32_16x16x32_bf16 v[2:5], v[206:209], v[238:241], v[2:5]
	v_mfma_f32_16x16x32_bf16 v[54:57], v[202:205], v[218:221], v[54:57]
	v_mfma_f32_16x16x32_bf16 v[50:53], v[210:213], v[218:221], v[50:53]
	v_mfma_f32_16x16x32_bf16 v[38:41], v[202:205], v[226:229], v[38:41]
	v_mfma_f32_16x16x32_bf16 v[34:37], v[210:213], v[226:229], v[34:37]
	v_mfma_f32_16x16x32_bf16 v[22:25], v[202:205], v[234:237], v[22:25]
	v_mfma_f32_16x16x32_bf16 v[18:21], v[210:213], v[234:237], v[18:21]
	v_mfma_f32_16x16x32_bf16 v[6:9], v[202:205], v[242:245], v[6:9]
	v_mfma_f32_16x16x32_bf16 v[2:5], v[210:213], v[242:245], v[2:5]
	s_setprio 0
	s_barrier
	s_cbranch_scc0 .Lgk_603
	s_and_b64 vcc, exec, s[40:41]
	s_cbranch_vccz .LBB0_606
	s_barrier

; #define PG8_STAGE(bufoff, gbase, voff) do { _Pragma("unroll") for (int _i = 0; _i < 2; ++_i) \
;         __builtin_amdgcn_global_load_lds((const unsigned*)((const char*)(gbase) + (voff)[_i]), (PG8_LAS unsigned*)(lds + (bufoff) + ldsw + _i * 8192), 16, 0, 0); } while (0)
; #define PG8_LDA(dst, b, h) do { _Pragma("unroll") for (int m = 0; m < 4; ++m) _Pragma("unroll") for (int k = 0; k < 2; ++k) dst[m][k] = *(const PG8_LAS bf16x8*)(lds + PG8_SA(b, h) + aoff + m * 2048 + k * 1024); } while (0)
; #define PG8_LDB(dst, b, h) do { _Pragma("unroll") for (int n = 0; n < 2; ++n) _Pragma("unroll") for (int k = 0; k < 2; ++k) dst[n][k] = *(const PG8_LAS bf16x8*)(lds + PG8_SB(b, h) + boff + n * 2048 + k * 1024); } while (0)
; #define PG8_MMA(ai, bj, At, Bt) do { __builtin_amdgcn_s_setprio(1); _Pragma("unroll") for (int m = 0; m < 4; ++m) _Pragma("unroll") for (int n = 0; n < 2; ++n) _Pragma("unroll") for (int k = 0; k < 2; ++k) \
;         acc[ai][bj][m][n] = __builtin_amdgcn_mfma_f32_16x16x32_bf16(Bt[n][k], At[m][k], acc[ai][bj][m][n], 0, 0, 0); __builtin_amdgcn_s_setprio(0); } while (0)
; #define PG8_WAIT_V(n) asm volatile("s_waitcnt vmcnt(" #n ")" ::: "memory")
; #define PG8_WAIT_L(n) asm volatile("s_waitcnt lgkmcnt(" #n ")" ::: "memory")
; #define PG8_BAR __builtin_amdgcn_s_barrier()
; #define PG8_SCHED __builtin_amdgcn_sched_barrier(0)
; template <class Epi, class Sched, bool ALIGN_EPI = false, bool SP2 = false>
; __device__ __forceinline__ void gemm_phase(PG8_LAS unsigned char* lds, const Gemm g, const Sched& S, const Epi& E) {
;     ...
;             PG8_LDB(B0, 0, 0); PG8_LDB(B1, 0, 1); PG8_SCHED; PG8_LDA(At, 0, 0); PG8_STAGE(PG8_SA(1, 1), a1 + hstepA, voffA);
;             PG8_WAIT_V(8); PG8_WAIT_L(0); PG8_BAR; PG8_MMA(0, 0, At, B0); PG8_MMA(0, 1, At, B1); PG8_BAR; PG8_SCHED;
;             PG8_LDA(At, 0, 1); PG8_STAGE(PG8_SB(0, 0), b2, voffB); PG8_STAGE(PG8_SB(0, 1), b2 + hstepB, voffB); PG8_STAGE(PG8_SA(0, 0), a2, voffA);
.Lgk_623:
	ds_read_b128 v[160:163], v130
	ds_read_b128 v[164:167], v130 offset:1024
	ds_read_b128 v[186:189], v130 offset:2048
	ds_read_b128 v[190:193], v130 offset:3072
	v_add_u32_e32 v130, s13, v169
	ds_read_b128 v[198:201], v130
	ds_read_b128 v[202:205], v130 offset:1024
	ds_read_b128 v[206:209], v130 offset:2048
	ds_read_b128 v[210:213], v130 offset:3072
	v_lshl_add_u64 v[130:131], s[54:55], 0, v[156:157]
	s_add_i32 m0, s53, 0xc000
	ds_read_b128 v[214:217], v171
	ds_read_b128 v[218:221], v171 offset:1024
	ds_read_b128 v[222:225], v171 offset:2048
	ds_read_b128 v[226:229], v171 offset:3072
	ds_read_b128 v[230:233], v171 offset:4096
	ds_read_b128 v[234:237], v171 offset:5120
	ds_read_b128 v[238:241], v171 offset:6144
	ds_read_b128 v[242:245], v171 offset:7168
	global_load_lds_dwordx4 v[130:131], off
	v_lshl_add_u64 v[130:131], s[54:55], 0, v[158:159]
	s_add_i32 m0, s53, 0xe000
	s_nop 0
	global_load_lds_dwordx4 v[130:131], off
	s_waitcnt vmcnt(8)
	s_waitcnt lgkmcnt(0)
	s_barrier
	s_setprio 1
	v_mfma_f32_16x16x32_bf16 v[126:129], v[160:163], v[214:217], v[126:129]
	v_mfma_f32_16x16x32_bf16 v[122:125], v[186:189], v[214:217], v[122:125]
	v_mfma_f32_16x16x32_bf16 v[110:113], v[160:163], v[222:225], v[110:113]
	v_mfma_f32_16x16x32_bf16 v[106:109], v[186:189], v[222:225], v[106:109]
	v_mfma_f32_16x16x32_bf16 v[94:97], v[160:163], v[230:233], v[94:97]
	v_mfma_f32_16x16x32_bf16 v[90:93], v[186:189], v[230:233], v[90:93]
	v_mfma_f32_16x16x32_bf16 v[78:81], v[160:163], v[238:241], v[78:81]
	v_mfma_f32_16x16x32_bf16 v[74:77], v[186:189], v[238:241], v[74:77]
	v_mfma_f32_16x16x32_bf16 v[126:129], v[164:167], v[218:221], v[126:129]
	v_mfma_f32_16x16x32_bf16 v[122:125], v[190:193], v[218:221], v[122:125]
	v_mfma_f32_16x16x32_bf16 v[110:113], v[164:167], v[226:229], v[110:113]
	v_mfma_f32_16x16x32_bf16 v[106:109], v[190:193], v[226:229], v[106:109]
	v_mfma_f32_16x16x32_bf16 v[94:97], v[164:167], v[234:237], v[94:97]
	v_mfma_f32_16x16x32_bf16 v[90:93], v[190:193], v[234:237], v[90:93]
	v_mfma_f32_16x16x32_bf16 v[78:81], v[164:167], v[242:245], v[78:81]
	v_mfma_f32_16x16x32_bf16 v[74:77], v[190:193], v[242:245], v[74:77]
	s_setprio 0
	s_setprio 1
	v_mfma_f32_16x16x32_bf16 v[118:121], v[198:201], v[214:217], v[118:121]
	v_mfma_f32_16x16x32_bf16 v[114:117], v[206:209], v[214:217], v[114:117]
	v_mfma_f32_16x16x32_bf16 v[102:105], v[198:201], v[222:225], v[102:105]
	v_mfma_f32_16x16x32_bf16 v[98:101], v[206:209], v[222:225], v[98:101]
	v_mfma_f32_16x16x32_bf16 v[86:89], v[198:201], v[230:233], v[86:89]
	v_mfma_f32_16x16x32_bf16 v[82:85], v[206:209], v[230:233], v[82:85]
	v_mfma_f32_16x16x32_bf16 v[70:73], v[198:201], v[238:241], v[70:73]
	v_mfma_f32_16x16x32_bf16 v[66:69], v[206:209], v[238:241], v[66:69]
	v_mfma_f32_16x16x32_bf16 v[118:121], v[202:205], v[218:221], v[118:121]
	v_mfma_f32_16x16x32_bf16 v[114:117], v[210:213], v[218:221], v[114:117]
	v_mfma_f32_16x16x32_bf16 v[102:105], v[202:205], v[226:229], v[102:105]
	v_mfma_f32_16x16x32_bf16 v[98:101], v[210:213], v[226:229], v[98:101]
	v_mfma_f32_16x16x32_bf16 v[86:89], v[202:205], v[234:237], v[86:89]
	v_mfma_f32_16x16x32_bf16 v[82:85], v[210:213], v[234:237], v[82:85]
	v_mfma_f32_16x16x32_bf16 v[70:73], v[202:205], v[242:245], v[70:73]
	v_mfma_f32_16x16x32_bf16 v[66:69], v[210:213], v[242:245], v[66:69]
	s_setprio 0
	s_barrier
	s_add_i32 s10, s12, s68
	v_lshl_add_u64 v[130:131], s[56:57], 0, v[0:1]
	s_mov_b32 m0, s10
	ds_read_b128 v[214:217], v171 offset:16384
	ds_read_b128 v[218:221], v171 offset:17408
	ds_read_b128 v[222:225], v171 offset:18432
	ds_read_b128 v[226:229], v171 offset:19456
	ds_read_b128 v[230:233], v171 offset:20480
	ds_read_b128 v[234:237], v171 offset:21504
	ds_read_b128 v[238:241], v171 offset:22528
	ds_read_b128 v[242:245], v171 offset:23552
	global_load_lds_dwordx4 v[130:131], off
	s_add_i32 m0, s10, 0x2000
	s_add_u32 s10, s56, 0x20000
	v_lshl_add_u64 v[132:133], s[56:57], 0, v[150:151]
	s_addc_u32 s11, s57, 0
	s_add_i32 s12, s13, s68
	global_load_lds_dwordx4 v[132:133], off
	v_lshl_add_u64 v[172:173], s[10:11], 0, v[0:1]
	s_mov_b32 m0, s12
	v_lshl_add_u64 v[246:247], s[62:63], 0, v[152:153]
	global_load_lds_dwordx4 v[172:173], off
	v_lshl_add_u64 v[172:173], s[10:11], 0, v[150:151]
	s_add_i32 m0, s12, 0x2000
	s_nop 0
	global_load_lds_dwordx4 v[172:173], off
	v_lshl_add_u64 v[172:173], s[62:63], 0, v[154:155]
	s_mov_b32 m0, s53
	s_nop 0
	global_load_lds_dwordx4 v[172:173], off
	s_mov_b32 m0, s69
	s_nop 0
	global_load_lds_dwordx4 v[246:247], off
	s_waitcnt vmcnt(8)
	s_waitcnt lgkmcnt(0)
	s_barrier
; #define PG8_STAGE(bufoff, gbase, voff) do { _Pragma("unroll") for (int _i = 0; _i < 2; ++_i) \
;         __builtin_amdgcn_global_load_lds((const unsigned*)((const char*)(gbase) + (voff)[_i]), (PG8_LAS unsigned*)(lds + (bufoff) + ldsw + _i * 8192), 16, 0, 0); } while (0)
; #define PG8_LDA(dst, b, h) do { _Pragma("unroll") for (int m = 0; m < 4; ++m) _Pragma("unroll") for (int k = 0; k < 2; ++k) dst[m][k] = *(const PG8_LAS bf16x8*)(lds + PG8_SA(b, h) + aoff + m * 2048 + k * 1024); } while (0)
; #define PG8_LDB(dst, b, h) do { _Pragma("unroll") for (int n = 0; n < 2; ++n) _Pragma("unroll") for (int k = 0; k < 2; ++k) dst[n][k] = *(const PG8_LAS bf16x8*)(lds + PG8_SB(b, h) + boff + n * 2048 + k * 1024); } while (0)
; #define PG8_MMA(ai, bj, At, Bt) do { __builtin_amdgcn_s_setprio(1); _Pragma("unroll") for (int m = 0; m < 4; ++m) _Pragma("unroll") for (int n = 0; n < 2; ++n) _Pragma("unroll") for (int k = 0; k < 2; ++k) \
;         acc[ai][bj][m][n] = __builtin_amdgcn_mfma_f32_16x16x32_bf16(Bt[n][k], At[m][k], acc[ai][bj][m][n], 0, 0, 0); __builtin_amdgcn_s_setprio(0); } while (0)
; #define PG8_WAIT_V(n) asm volatile("s_waitcnt vmcnt(" #n ")" ::: "memory")
; #define PG8_WAIT_L(n) asm volatile("s_waitcnt lgkmcnt(" #n ")" ::: "memory")
; #define PG8_BAR __builtin_amdgcn_s_barrier()
; #define PG8_SCHED __builtin_amdgcn_sched_barrier(0)
; template <class Epi, class Sched, bool ALIGN_EPI = false, bool SP2 = false>
; __device__ __forceinline__ void gemm_phase(PG8_LAS unsigned char* lds, const Gemm g, const Sched& S, const Epi& E) {
;     ...
;             PG8_WAIT_V(8); PG8_WAIT_L(0); PG8_BAR; PG8_MMA(1, 0, At, B0); PG8_MMA(1, 1, At, B1); PG8_BAR; PG8_SCHED;
;             PG8_LDB(B0, 1, 0); PG8_LDB(B1, 1, 1); PG8_SCHED; PG8_LDA(At, 1, 0); PG8_STAGE(PG8_SA(0, 1), a2 + hstepA, voffA);
;             PG8_WAIT_V(8); PG8_WAIT_L(0); PG8_BAR; PG8_MMA(0, 0, At, B0); PG8_MMA(0, 1, At, B1); PG8_BAR; PG8_SCHED;
	s_setprio 1
	v_mfma_f32_16x16x32_bf16 v[62:65], v[160:163], v[214:217], v[62:65]
	v_mfma_f32_16x16x32_bf16 v[58:61], v[186:189], v[214:217], v[58:61]
	v_mfma_f32_16x16x32_bf16 v[46:49], v[160:163], v[222:225], v[46:49]
	v_mfma_f32_16x16x32_bf16 v[42:45], v[186:189], v[222:225], v[42:45]
	v_mfma_f32_16x16x32_bf16 v[30:33], v[160:163], v[230:233], v[30:33]
	v_mfma_f32_16x16x32_bf16 v[26:29], v[186:189], v[230:233], v[26:29]
	v_mfma_f32_16x16x32_bf16 v[14:17], v[160:163], v[238:241], v[14:17]
	v_mfma_f32_16x16x32_bf16 v[10:13], v[186:189], v[238:241], v[10:13]
	v_mfma_f32_16x16x32_bf16 v[62:65], v[164:167], v[218:221], v[62:65]
	v_mfma_f32_16x16x32_bf16 v[58:61], v[190:193], v[218:221], v[58:61]
	v_mfma_f32_16x16x32_bf16 v[46:49], v[164:167], v[226:229], v[46:49]
	v_mfma_f32_16x16x32_bf16 v[42:45], v[190:193], v[226:229], v[42:45]
	v_mfma_f32_16x16x32_bf16 v[30:33], v[164:167], v[234:237], v[30:33]
	v_mfma_f32_16x16x32_bf16 v[26:29], v[190:193], v[234:237], v[26:29]
	v_mfma_f32_16x16x32_bf16 v[14:17], v[164:167], v[242:245], v[14:17]
	v_mfma_f32_16x16x32_bf16 v[10:13], v[190:193], v[242:245], v[10:13]
	s_setprio 0
	s_setprio 1
	v_mfma_f32_16x16x32_bf16 v[54:57], v[198:201], v[214:217], v[54:57]
	v_mfma_f32_16x16x32_bf16 v[50:53], v[206:209], v[214:217], v[50:53]
	v_mfma_f32_16x16x32_bf16 v[38:41], v[198:201], v[222:225], v[38:41]
	v_mfma_f32_16x16x32_bf16 v[34:37], v[206:209], v[222:225], v[34:37]
	v_mfma_f32_16x16x32_bf16 v[22:25], v[198:201], v[230:233], v[22:25]
	v_mfma_f32_16x16x32_bf16 v[18:21], v[206:209], v[230:233], v[18:21]
	v_mfma_f32_16x16x32_bf16 v[6:9], v[198:201], v[238:241], v[6:9]
	v_mfma_f32_16x16x32_bf16 v[2:5], v[206:209], v[238:241], v[2:5]
	v_mfma_f32_16x16x32_bf16 v[54:57], v[202:205], v[218:221], v[54:57]
	v_mfma_f32_16x16x32_bf16 v[50:53], v[210:213], v[218:221], v[50:53]
	v_mfma_f32_16x16x32_bf16 v[38:41], v[202:205], v[226:229], v[38:41]
	v_mfma_f32_16x16x32_bf16 v[34:37], v[210:213], v[226:229], v[34:37]
	v_mfma_f32_16x16x32_bf16 v[22:25], v[202:205], v[234:237], v[22:25]
	v_mfma_f32_16x16x32_bf16 v[18:21], v[210:213], v[234:237], v[18:21]
	v_mfma_f32_16x16x32_bf16 v[6:9], v[202:205], v[242:245], v[6:9]
	v_mfma_f32_16x16x32_bf16 v[2:5], v[210:213], v[242:245], v[2:5]
	s_setprio 0
	s_barrier
	s_add_i32 s12, 0, 0x18000
	s_add_i32 s13, 0, 0x1c000
	v_add_u32_e32 v190, s12, v169
	v_add_u32_e32 v210, s13, v169
	ds_read_b128 v[160:163], v190
	ds_read_b128 v[164:167], v190 offset:1024
	ds_read_b128 v[186:189], v190 offset:2048
	ds_read_b128 v[190:193], v190 offset:3072
	ds_read_b128 v[198:201], v210
	ds_read_b128 v[202:205], v210 offset:1024
	ds_read_b128 v[206:209], v210 offset:2048
	ds_read_b128 v[210:213], v210 offset:3072
	s_add_u32 s10, s62, 0x20000
	s_addc_u32 s11, s63, 0
	s_mov_b32 m0, s94
	v_lshl_add_u64 v[248:249], s[10:11], 0, v[154:155]
	ds_read_b128 v[214:217], v171 offset:32768
	ds_read_b128 v[218:221], v171 offset:33792
	ds_read_b128 v[222:225], v171 offset:34816
	ds_read_b128 v[226:229], v171 offset:35840
	ds_read_b128 v[230:233], v171 offset:36864
	ds_read_b128 v[234:237], v171 offset:37888
	ds_read_b128 v[238:241], v171 offset:38912
	ds_read_b128 v[242:245], v171 offset:39936
	global_load_lds_dwordx4 v[248:249], off
	v_lshl_add_u64 v[248:249], s[10:11], 0, v[152:153]
	s_mov_b32 m0, s95
	s_nop 0
	global_load_lds_dwordx4 v[248:249], off
	s_waitcnt vmcnt(8)
	s_waitcnt lgkmcnt(0)
	s_barrier
	s_setprio 1
	v_mfma_f32_16x16x32_bf16 v[126:129], v[160:163], v[214:217], v[126:129]
	v_mfma_f32_16x16x32_bf16 v[122:125], v[186:189], v[214:217], v[122:125]
	v_mfma_f32_16x16x32_bf16 v[110:113], v[160:163], v[222:225], v[110:113]
	v_mfma_f32_16x16x32_bf16 v[106:109], v[186:189], v[222:225], v[106:109]
	v_mfma_f32_16x16x32_bf16 v[94:97], v[160:163], v[230:233], v[94:97]
	v_mfma_f32_16x16x32_bf16 v[90:93], v[186:189], v[230:233], v[90:93]
	v_mfma_f32_16x16x32_bf16 v[78:81], v[160:163], v[238:241], v[78:81]
	v_mfma_f32_16x16x32_bf16 v[74:77], v[186:189], v[238:241], v[74:77]
	v_mfma_f32_16x16x32_bf16 v[126:129], v[164:167], v[218:221], v[126:129]
	v_mfma_f32_16x16x32_bf16 v[122:125], v[190:193], v[218:221], v[122:125]
	v_mfma_f32_16x16x32_bf16 v[110:113], v[164:167], v[226:229], v[110:113]
	v_mfma_f32_16x16x32_bf16 v[106:109], v[190:193], v[226:229], v[106:109]
	v_mfma_f32_16x16x32_bf16 v[94:97], v[164:167], v[234:237], v[94:97]
	v_mfma_f32_16x16x32_bf16 v[90:93], v[190:193], v[234:237], v[90:93]
	v_mfma_f32_16x16x32_bf16 v[78:81], v[164:167], v[242:245], v[78:81]
	v_mfma_f32_16x16x32_bf16 v[74:77], v[190:193], v[242:245], v[74:77]
	s_setprio 0
	s_setprio 1
	v_mfma_f32_16x16x32_bf16 v[118:121], v[198:201], v[214:217], v[118:121]
	v_mfma_f32_16x16x32_bf16 v[114:117], v[206:209], v[214:217], v[114:117]
	v_mfma_f32_16x16x32_bf16 v[102:105], v[198:201], v[222:225], v[102:105]
	v_mfma_f32_16x16x32_bf16 v[98:101], v[206:209], v[222:225], v[98:101]
	v_mfma_f32_16x16x32_bf16 v[86:89], v[198:201], v[230:233], v[86:89]
	v_mfma_f32_16x16x32_bf16 v[82:85], v[206:209], v[230:233], v[82:85]
	v_mfma_f32_16x16x32_bf16 v[70:73], v[198:201], v[238:241], v[70:73]
	v_mfma_f32_16x16x32_bf16 v[66:69], v[206:209], v[238:241], v[66:69]
	v_mfma_f32_16x16x32_bf16 v[118:121], v[202:205], v[218:221], v[118:121]
	v_mfma_f32_16x16x32_bf16 v[114:117], v[210:213], v[218:221], v[114:117]
	v_mfma_f32_16x16x32_bf16 v[102:105], v[202:205], v[226:229], v[102:105]
	v_mfma_f32_16x16x32_bf16 v[98:101], v[210:213], v[226:229], v[98:101]
	v_mfma_f32_16x16x32_bf16 v[86:89], v[202:205], v[234:237], v[86:89]
	v_mfma_f32_16x16x32_bf16 v[82:85], v[210:213], v[234:237], v[82:85]
	v_mfma_f32_16x16x32_bf16 v[70:73], v[202:205], v[242:245], v[70:73]
	v_mfma_f32_16x16x32_bf16 v[66:69], v[210:213], v[242:245], v[66:69]
	s_setprio 0
	s_barrier
; #define PG8_STAGE(bufoff, gbase, voff) do { _Pragma("unroll") for (int _i = 0; _i < 2; ++_i) \
;         __builtin_amdgcn_global_load_lds((const unsigned*)((const char*)(gbase) + (voff)[_i]), (PG8_LAS unsigned*)(lds + (bufoff) + ldsw + _i * 8192), 16, 0, 0); } while (0)
; #define PG8_LDA(dst, b, h) do { _Pragma("unroll") for (int m = 0; m < 4; ++m) _Pragma("unroll") for (int k = 0; k < 2; ++k) dst[m][k] = *(const PG8_LAS bf16x8*)(lds + PG8_SA(b, h) + aoff + m * 2048 + k * 1024); } while (0)
; #define PG8_MMA(ai, bj, At, Bt) do { __builtin_amdgcn_s_setprio(1); _Pragma("unroll") for (int m = 0; m < 4; ++m) _Pragma("unroll") for (int n = 0; n < 2; ++n) _Pragma("unroll") for (int k = 0; k < 2; ++k) \
;         acc[ai][bj][m][n] = __builtin_amdgcn_mfma_f32_16x16x32_bf16(Bt[n][k], At[m][k], acc[ai][bj][m][n], 0, 0, 0); __builtin_amdgcn_s_setprio(0); } while (0)
; #define PG8_WAIT_V(n) asm volatile("s_waitcnt vmcnt(" #n ")" ::: "memory")
; #define PG8_WAIT_L(n) asm volatile("s_waitcnt lgkmcnt(" #n ")" ::: "memory")
; #define PG8_BAR __builtin_amdgcn_s_barrier()
; #define PG8_SCHED __builtin_amdgcn_sched_barrier(0)
; template <class Epi, class Sched, bool ALIGN_EPI = false, bool SP2 = false>
; __device__ __forceinline__ void gemm_phase(PG8_LAS unsigned char* lds, const Gemm g, const Sched& S, const Epi& E) {
;     ...
;             const bool last = (t == nt - 2);
;             const char* a1 = cA + (size_t)(t + 1) * kstep;
;             const char* a2 = last ? nA : cA + (size_t)(t + 2) * kstep; const char* b2 = last ? nB : cB + (size_t)(t + 2) * kstep;
;             const char* a3 = a2 + kstep; const char* b3 = b2 + kstep;
;     ...
;             PG8_LDA(At, 1, 1); PG8_STAGE(PG8_SB(1, 0), b3, voffB); PG8_STAGE(PG8_SB(1, 1), b3 + hstepB, voffB); PG8_STAGE(PG8_SA(1, 0), a3, voffA);
;             PG8_WAIT_V(8); PG8_WAIT_L(0); PG8_BAR; PG8_MMA(1, 0, At, B0); PG8_MMA(1, 1, At, B1); PG8_BAR; PG8_SCHED;
	s_add_i32 s10, s12, s68
	v_lshl_add_u64 v[130:131], v[130:131], 0, s[2:3]
	s_mov_b32 m0, s10
	ds_read_b128 v[214:217], v171 offset:49152
	ds_read_b128 v[218:221], v171 offset:50176
	ds_read_b128 v[222:225], v171 offset:51200
	ds_read_b128 v[226:229], v171 offset:52224
	ds_read_b128 v[230:233], v171 offset:53248
	ds_read_b128 v[234:237], v171 offset:54272
	ds_read_b128 v[238:241], v171 offset:55296
	ds_read_b128 v[242:245], v171 offset:56320
	global_load_lds_dwordx4 v[130:131], off
	s_add_i32 m0, s10, 0x2000
	s_add_u32 s10, s56, 0x20080
	v_lshl_add_u64 v[130:131], v[132:133], 0, s[2:3]
	s_addc_u32 s11, s57, 0
	s_add_i32 s12, s13, s68
	global_load_lds_dwordx4 v[130:131], off
	v_lshl_add_u64 v[130:131], s[10:11], 0, v[0:1]
	s_mov_b32 m0, s12
	s_nop 0
	global_load_lds_dwordx4 v[130:131], off
	v_lshl_add_u64 v[130:131], s[10:11], 0, v[150:151]
	s_add_i32 m0, s12, 0x2000
	s_nop 0
	global_load_lds_dwordx4 v[130:131], off
	v_lshl_add_u64 v[130:131], v[172:173], 0, s[2:3]
	s_mov_b32 m0, s8
	s_nop 0
	global_load_lds_dwordx4 v[130:131], off
	v_lshl_add_u64 v[130:131], v[246:247], 0, s[2:3]
	s_mov_b32 m0, s9
	s_nop 0
	global_load_lds_dwordx4 v[130:131], off
	s_waitcnt vmcnt(8)
	s_waitcnt lgkmcnt(0)
	s_barrier
	s_setprio 1
	v_mfma_f32_16x16x32_bf16 v[62:65], v[160:163], v[214:217], v[62:65]
	v_mfma_f32_16x16x32_bf16 v[58:61], v[186:189], v[214:217], v[58:61]
	s_add_i32 vcc_hi, vcc_hi, 2
	v_mfma_f32_16x16x32_bf16 v[46:49], v[160:163], v[222:225], v[46:49]
	s_add_u32 s54, s54, 0x100
	v_mfma_f32_16x16x32_bf16 v[42:45], v[186:189], v[222:225], v[42:45]
	s_addc_u32 s55, s55, 0
	v_mfma_f32_16x16x32_bf16 v[30:33], v[160:163], v[230:233], v[30:33]
	s_add_u32 s91, s91, 0x100
	v_mfma_f32_16x16x32_bf16 v[26:29], v[186:189], v[230:233], v[26:29]
	s_addc_u32 vcc_lo, vcc_lo, 0
	v_mfma_f32_16x16x32_bf16 v[14:17], v[160:163], v[238:241], v[14:17]
	s_add_u32 s10, s54, 0xfffe0080
	v_mfma_f32_16x16x32_bf16 v[10:13], v[186:189], v[238:241], v[10:13]
	s_addc_u32 s11, s55, -1
	v_mfma_f32_16x16x32_bf16 v[62:65], v[164:167], v[218:221], v[62:65]
	s_add_i32 s12, 0, 0x10000
	v_mfma_f32_16x16x32_bf16 v[58:61], v[190:193], v[218:221], v[58:61]
	s_cmp_eq_u32 vcc_hi, 4
	v_mfma_f32_16x16x32_bf16 v[46:49], v[164:167], v[226:229], v[46:49]
	s_cselect_b32 s63, s41, s11
	v_mfma_f32_16x16x32_bf16 v[42:45], v[190:193], v[226:229], v[42:45]
	s_cselect_b32 s62, s47, s10
	v_mfma_f32_16x16x32_bf16 v[30:33], v[164:167], v[234:237], v[30:33]
	v_add_u32_e32 v130, s12, v169
	v_mfma_f32_16x16x32_bf16 v[26:29], v[190:193], v[234:237], v[26:29]
	s_cselect_b32 s57, s4, vcc_lo
	v_mfma_f32_16x16x32_bf16 v[14:17], v[164:167], v[242:245], v[14:17]
	s_cselect_b32 s56, s45, s91
	v_mfma_f32_16x16x32_bf16 v[10:13], v[190:193], v[242:245], v[10:13]
	s_add_i32 s13, 0, 0x14000
	s_setprio 0
	s_setprio 1
	v_mfma_f32_16x16x32_bf16 v[54:57], v[198:201], v[214:217], v[54:57]
	s_cmp_gt_u32 vcc_hi, 5
	v_mfma_f32_16x16x32_bf16 v[50:53], v[206:209], v[214:217], v[50:53]
	v_mfma_f32_16x16x32_bf16 v[38:41], v[198:201], v[222:225], v[38:41]
	v_mfma_f32_16x16x32_bf16 v[34:37], v[206:209], v[222:225], v[34:37]
	v_mfma_f32_16x16x32_bf16 v[22:25], v[198:201], v[230:233], v[22:25]
	v_mfma_f32_16x16x32_bf16 v[18:21], v[206:209], v[230:233], v[18:21]
	v_mfma_f32_16x16x32_bf16 v[6:9], v[198:201], v[238:241], v[6:9]
	v_mfma_f32_16x16x32_bf16 v[2:5], v[206:209], v[238:241], v[2:5]
	v_mfma_f32_16x16x32_bf16 v[54:57], v[202:205], v[218:221], v[54:57]
	v_mfma_f32_16x16x32_bf16 v[50:53], v[210:213], v[218:221], v[50:53]
	v_mfma_f32_16x16x32_bf16 v[38:41], v[202:205], v[226:229], v[38:41]
	v_mfma_f32_16x16x32_bf16 v[34:37], v[210:213], v[226:229], v[34:37]
	v_mfma_f32_16x16x32_bf16 v[22:25], v[202:205], v[234:237], v[22:25]
	v_mfma_f32_16x16x32_bf16 v[18:21], v[210:213], v[234:237], v[18:21]
	v_mfma_f32_16x16x32_bf16 v[6:9], v[202:205], v[242:245], v[6:9]
	v_mfma_f32_16x16x32_bf16 v[2:5], v[210:213], v[242:245], v[2:5]
	s_setprio 0
	s_barrier
	s_cbranch_scc0 .Lgk_623
	s_and_b64 vcc, exec, s[42:43]
	s_cbranch_vccz .LBB0_626
	s_barrier

; #define PG8_STAGE(bufoff, gbase, voff) do { _Pragma("unroll") for (int _i = 0; _i < 2; ++_i) \
;         __builtin_amdgcn_global_load_lds((const unsigned*)((const char*)(gbase) + (voff)[_i]), (PG8_LAS unsigned*)(lds + (bufoff) + ldsw + _i * 8192), 16, 0, 0); } while (0)
; #define PG8_LDA(dst, b, h) do { _Pragma("unroll") for (int m = 0; m < 4; ++m) _Pragma("unroll") for (int k = 0; k < 2; ++k) dst[m][k] = *(const PG8_LAS bf16x8*)(lds + PG8_SA(b, h) + aoff + m * 2048 + k * 1024); } while (0)
; #define PG8_LDB(dst, b, h) do { _Pragma("unroll") for (int n = 0; n < 2; ++n) _Pragma("unroll") for (int k = 0; k < 2; ++k) dst[n][k] = *(const PG8_LAS bf16x8*)(lds + PG8_SB(b, h) + boff + n * 2048 + k * 1024); } while (0)
; #define PG8_MMA(ai, bj, At, Bt) do { __builtin_amdgcn_s_setprio(1); _Pragma("unroll") for (int m = 0; m < 4; ++m) _Pragma("unroll") for (int n = 0; n < 2; ++n) _Pragma("unroll") for (int k = 0; k < 2; ++k) \
;         acc[ai][bj][m][n] = __builtin_amdgcn_mfma_f32_16x16x32_bf16(Bt[n][k], At[m][k], acc[ai][bj][m][n], 0, 0, 0); __builtin_amdgcn_s_setprio(0); } while (0)
; #define PG8_WAIT_V(n) asm volatile("s_waitcnt vmcnt(" #n ")" ::: "memory")
; #define PG8_WAIT_L(n) asm volatile("s_waitcnt lgkmcnt(" #n ")" ::: "memory")
; #define PG8_BAR __builtin_amdgcn_s_barrier()
; #define PG8_SCHED __builtin_amdgcn_sched_barrier(0)
; template <class Epi, class Sched, bool ALIGN_EPI = false, bool SP2 = false>
; __device__ __forceinline__ void gemm_phase(PG8_LAS unsigned char* lds, const Gemm g, const Sched& S, const Epi& E) {
;     ...
;             PG8_LDB(B0, 0, 0); PG8_LDB(B1, 0, 1); PG8_SCHED; PG8_LDA(At, 0, 0); PG8_STAGE(PG8_SA(1, 1), a1 + hstepA, voffA);
;             PG8_WAIT_V(8); PG8_WAIT_L(0); PG8_BAR; PG8_MMA(0, 0, At, B0); PG8_MMA(0, 1, At, B1); PG8_BAR; PG8_SCHED;
;             PG8_LDA(At, 0, 1); PG8_STAGE(PG8_SB(0, 0), b2, voffB); PG8_STAGE(PG8_SB(0, 1), b2 + hstepB, voffB); PG8_STAGE(PG8_SA(0, 0), a2, voffA);
.Lgk_929:
	ds_read_b128 v[160:163], v130
	ds_read_b128 v[170:173], v130 offset:1024
	ds_read_b128 v[186:189], v130 offset:2048
	ds_read_b128 v[190:193], v130 offset:3072
	v_add_u32_e32 v130, s13, v167
	ds_read_b128 v[198:201], v130
	ds_read_b128 v[202:205], v130 offset:1024
	ds_read_b128 v[206:209], v130 offset:2048
	ds_read_b128 v[210:213], v130 offset:3072
	v_lshl_add_u64 v[130:131], s[46:47], 0, v[156:157]
	s_add_i32 m0, s9, 0xc000
	ds_read_b128 v[214:217], v169
	ds_read_b128 v[218:221], v169 offset:1024
	ds_read_b128 v[222:225], v169 offset:2048
	ds_read_b128 v[226:229], v169 offset:3072
	ds_read_b128 v[230:233], v169 offset:4096
	ds_read_b128 v[234:237], v169 offset:5120
	ds_read_b128 v[238:241], v169 offset:6144
	ds_read_b128 v[242:245], v169 offset:7168
	global_load_lds_dwordx4 v[130:131], off
	v_lshl_add_u64 v[130:131], s[46:47], 0, v[158:159]
	s_add_i32 m0, s9, 0xe000
	s_nop 0
	global_load_lds_dwordx4 v[130:131], off
	s_waitcnt vmcnt(8)
	s_waitcnt lgkmcnt(0)
	s_barrier
	s_setprio 1
	v_mfma_f32_16x16x32_bf16 v[126:129], v[160:163], v[214:217], v[126:129]
	v_mfma_f32_16x16x32_bf16 v[122:125], v[186:189], v[214:217], v[122:125]
	v_mfma_f32_16x16x32_bf16 v[110:113], v[160:163], v[222:225], v[110:113]
	v_mfma_f32_16x16x32_bf16 v[106:109], v[186:189], v[222:225], v[106:109]
	v_mfma_f32_16x16x32_bf16 v[94:97], v[160:163], v[230:233], v[94:97]
	v_mfma_f32_16x16x32_bf16 v[90:93], v[186:189], v[230:233], v[90:93]
	v_mfma_f32_16x16x32_bf16 v[78:81], v[160:163], v[238:241], v[78:81]
	v_mfma_f32_16x16x32_bf16 v[74:77], v[186:189], v[238:241], v[74:77]
	v_mfma_f32_16x16x32_bf16 v[126:129], v[170:173], v[218:221], v[126:129]
	v_mfma_f32_16x16x32_bf16 v[122:125], v[190:193], v[218:221], v[122:125]
	v_mfma_f32_16x16x32_bf16 v[110:113], v[170:173], v[226:229], v[110:113]
	v_mfma_f32_16x16x32_bf16 v[106:109], v[190:193], v[226:229], v[106:109]
	v_mfma_f32_16x16x32_bf16 v[94:97], v[170:173], v[234:237], v[94:97]
	v_mfma_f32_16x16x32_bf16 v[90:93], v[190:193], v[234:237], v[90:93]
	v_mfma_f32_16x16x32_bf16 v[78:81], v[170:173], v[242:245], v[78:81]
	v_mfma_f32_16x16x32_bf16 v[74:77], v[190:193], v[242:245], v[74:77]
	s_setprio 0
	s_setprio 1
	v_mfma_f32_16x16x32_bf16 v[118:121], v[198:201], v[214:217], v[118:121]
	v_mfma_f32_16x16x32_bf16 v[114:117], v[206:209], v[214:217], v[114:117]
	v_mfma_f32_16x16x32_bf16 v[102:105], v[198:201], v[222:225], v[102:105]
	v_mfma_f32_16x16x32_bf16 v[98:101], v[206:209], v[222:225], v[98:101]
	v_mfma_f32_16x16x32_bf16 v[86:89], v[198:201], v[230:233], v[86:89]
	v_mfma_f32_16x16x32_bf16 v[82:85], v[206:209], v[230:233], v[82:85]
	v_mfma_f32_16x16x32_bf16 v[70:73], v[198:201], v[238:241], v[70:73]
	v_mfma_f32_16x16x32_bf16 v[66:69], v[206:209], v[238:241], v[66:69]
	v_mfma_f32_16x16x32_bf16 v[118:121], v[202:205], v[218:221], v[118:121]
	v_mfma_f32_16x16x32_bf16 v[114:117], v[210:213], v[218:221], v[114:117]
	v_mfma_f32_16x16x32_bf16 v[102:105], v[202:205], v[226:229], v[102:105]
	v_mfma_f32_16x16x32_bf16 v[98:101], v[210:213], v[226:229], v[98:101]
	v_mfma_f32_16x16x32_bf16 v[86:89], v[202:205], v[234:237], v[86:89]
	v_mfma_f32_16x16x32_bf16 v[82:85], v[210:213], v[234:237], v[82:85]
	v_mfma_f32_16x16x32_bf16 v[70:73], v[202:205], v[242:245], v[70:73]
	v_mfma_f32_16x16x32_bf16 v[66:69], v[210:213], v[242:245], v[66:69]
	s_setprio 0
	s_barrier
	s_add_i32 s10, s12, s8
	v_lshl_add_u64 v[130:131], s[48:49], 0, v[0:1]
	s_mov_b32 m0, s10
	ds_read_b128 v[214:217], v169 offset:16384
	ds_read_b128 v[218:221], v169 offset:17408
	ds_read_b128 v[222:225], v169 offset:18432
	ds_read_b128 v[226:229], v169 offset:19456
	ds_read_b128 v[230:233], v169 offset:20480
	ds_read_b128 v[234:237], v169 offset:21504
	ds_read_b128 v[238:241], v169 offset:22528
	ds_read_b128 v[242:245], v169 offset:23552
	global_load_lds_dwordx4 v[130:131], off
	s_add_i32 m0, s10, 0x2000
	s_add_u32 s10, s48, 0x100000
	v_lshl_add_u64 v[132:133], s[48:49], 0, v[150:151]
	s_addc_u32 s11, s49, 0
	s_add_i32 s12, s13, s8
	global_load_lds_dwordx4 v[132:133], off
	v_lshl_add_u64 v[164:165], s[10:11], 0, v[0:1]
	s_mov_b32 m0, s12
	v_lshl_add_u64 v[246:247], s[50:51], 0, v[152:153]
	global_load_lds_dwordx4 v[164:165], off
	v_lshl_add_u64 v[164:165], s[10:11], 0, v[150:151]
	s_add_i32 m0, s12, 0x2000
	s_nop 0
	global_load_lds_dwordx4 v[164:165], off
	v_lshl_add_u64 v[164:165], s[50:51], 0, v[154:155]
	s_mov_b32 m0, s9
	s_nop 0
	global_load_lds_dwordx4 v[164:165], off
	s_mov_b32 m0, s30
	s_nop 0
	global_load_lds_dwordx4 v[246:247], off
	s_waitcnt vmcnt(8)
	s_waitcnt lgkmcnt(0)
	s_barrier
; #define PG8_STAGE(bufoff, gbase, voff) do { _Pragma("unroll") for (int _i = 0; _i < 2; ++_i) \
;         __builtin_amdgcn_global_load_lds((const unsigned*)((const char*)(gbase) + (voff)[_i]), (PG8_LAS unsigned*)(lds + (bufoff) + ldsw + _i * 8192), 16, 0, 0); } while (0)
; #define PG8_LDA(dst, b, h) do { _Pragma("unroll") for (int m = 0; m < 4; ++m) _Pragma("unroll") for (int k = 0; k < 2; ++k) dst[m][k] = *(const PG8_LAS bf16x8*)(lds + PG8_SA(b, h) + aoff + m * 2048 + k * 1024); } while (0)
; #define PG8_LDB(dst, b, h) do { _Pragma("unroll") for (int n = 0; n < 2; ++n) _Pragma("unroll") for (int k = 0; k < 2; ++k) dst[n][k] = *(const PG8_LAS bf16x8*)(lds + PG8_SB(b, h) + boff + n * 2048 + k * 1024); } while (0)
; #define PG8_MMA(ai, bj, At, Bt) do { __builtin_amdgcn_s_setprio(1); _Pragma("unroll") for (int m = 0; m < 4; ++m) _Pragma("unroll") for (int n = 0; n < 2; ++n) _Pragma("unroll") for (int k = 0; k < 2; ++k) \
;         acc[ai][bj][m][n] = __builtin_amdgcn_mfma_f32_16x16x32_bf16(Bt[n][k], At[m][k], acc[ai][bj][m][n], 0, 0, 0); __builtin_amdgcn_s_setprio(0); } while (0)
; #define PG8_WAIT_V(n) asm volatile("s_waitcnt vmcnt(" #n ")" ::: "memory")
; #define PG8_WAIT_L(n) asm volatile("s_waitcnt lgkmcnt(" #n ")" ::: "memory")
; #define PG8_BAR __builtin_amdgcn_s_barrier()
; #define PG8_SCHED __builtin_amdgcn_sched_barrier(0)
; template <class Epi, class Sched, bool ALIGN_EPI = false, bool SP2 = false>
; __device__ __forceinline__ void gemm_phase(PG8_LAS unsigned char* lds, const Gemm g, const Sched& S, const Epi& E) {
;     ...
;             PG8_WAIT_V(8); PG8_WAIT_L(0); PG8_BAR; PG8_MMA(1, 0, At, B0); PG8_MMA(1, 1, At, B1); PG8_BAR; PG8_SCHED;
;             PG8_LDB(B0, 1, 0); PG8_LDB(B1, 1, 1); PG8_SCHED; PG8_LDA(At, 1, 0); PG8_STAGE(PG8_SA(0, 1), a2 + hstepA, voffA);
;             PG8_WAIT_V(8); PG8_WAIT_L(0); PG8_BAR; PG8_MMA(0, 0, At, B0); PG8_MMA(0, 1, At, B1); PG8_BAR; PG8_SCHED;
	s_setprio 1
	v_mfma_f32_16x16x32_bf16 v[62:65], v[160:163], v[214:217], v[62:65]
	v_mfma_f32_16x16x32_bf16 v[58:61], v[186:189], v[214:217], v[58:61]
	v_mfma_f32_16x16x32_bf16 v[46:49], v[160:163], v[222:225], v[46:49]
	v_mfma_f32_16x16x32_bf16 v[42:45], v[186:189], v[222:225], v[42:45]
	v_mfma_f32_16x16x32_bf16 v[30:33], v[160:163], v[230:233], v[30:33]
	v_mfma_f32_16x16x32_bf16 v[26:29], v[186:189], v[230:233], v[26:29]
	v_mfma_f32_16x16x32_bf16 v[14:17], v[160:163], v[238:241], v[14:17]
	v_mfma_f32_16x16x32_bf16 v[10:13], v[186:189], v[238:241], v[10:13]
	v_mfma_f32_16x16x32_bf16 v[62:65], v[170:173], v[218:221], v[62:65]
	v_mfma_f32_16x16x32_bf16 v[58:61], v[190:193], v[218:221], v[58:61]
	v_mfma_f32_16x16x32_bf16 v[46:49], v[170:173], v[226:229], v[46:49]
	v_mfma_f32_16x16x32_bf16 v[42:45], v[190:193], v[226:229], v[42:45]
	v_mfma_f32_16x16x32_bf16 v[30:33], v[170:173], v[234:237], v[30:33]
	v_mfma_f32_16x16x32_bf16 v[26:29], v[190:193], v[234:237], v[26:29]
	v_mfma_f32_16x16x32_bf16 v[14:17], v[170:173], v[242:245], v[14:17]
	v_mfma_f32_16x16x32_bf16 v[10:13], v[190:193], v[242:245], v[10:13]
	s_setprio 0
	s_setprio 1
	v_mfma_f32_16x16x32_bf16 v[54:57], v[198:201], v[214:217], v[54:57]
	v_mfma_f32_16x16x32_bf16 v[50:53], v[206:209], v[214:217], v[50:53]
	v_mfma_f32_16x16x32_bf16 v[38:41], v[198:201], v[222:225], v[38:41]
	v_mfma_f32_16x16x32_bf16 v[34:37], v[206:209], v[222:225], v[34:37]
	v_mfma_f32_16x16x32_bf16 v[22:25], v[198:201], v[230:233], v[22:25]
	v_mfma_f32_16x16x32_bf16 v[18:21], v[206:209], v[230:233], v[18:21]
	v_mfma_f32_16x16x32_bf16 v[6:9], v[198:201], v[238:241], v[6:9]
	v_mfma_f32_16x16x32_bf16 v[2:5], v[206:209], v[238:241], v[2:5]
	v_mfma_f32_16x16x32_bf16 v[54:57], v[202:205], v[218:221], v[54:57]
	v_mfma_f32_16x16x32_bf16 v[50:53], v[210:213], v[218:221], v[50:53]
	v_mfma_f32_16x16x32_bf16 v[38:41], v[202:205], v[226:229], v[38:41]
	v_mfma_f32_16x16x32_bf16 v[34:37], v[210:213], v[226:229], v[34:37]
	v_mfma_f32_16x16x32_bf16 v[22:25], v[202:205], v[234:237], v[22:25]
	v_mfma_f32_16x16x32_bf16 v[18:21], v[210:213], v[234:237], v[18:21]
	v_mfma_f32_16x16x32_bf16 v[6:9], v[202:205], v[242:245], v[6:9]
	v_mfma_f32_16x16x32_bf16 v[2:5], v[210:213], v[242:245], v[2:5]
	s_setprio 0
	s_barrier
	s_add_i32 s12, 0, 0x18000
	s_add_i32 s13, 0, 0x1c000
	v_add_u32_e32 v190, s12, v167
	v_add_u32_e32 v210, s13, v167
	ds_read_b128 v[160:163], v190
	ds_read_b128 v[170:173], v190 offset:1024
	ds_read_b128 v[186:189], v190 offset:2048
	ds_read_b128 v[190:193], v190 offset:3072
	ds_read_b128 v[198:201], v210
	ds_read_b128 v[202:205], v210 offset:1024
	ds_read_b128 v[206:209], v210 offset:2048
	ds_read_b128 v[210:213], v210 offset:3072
	s_add_u32 s10, s50, 0x100000
	s_addc_u32 s11, s51, 0
	s_mov_b32 m0, s31
	v_lshl_add_u64 v[248:249], s[10:11], 0, v[154:155]
	ds_read_b128 v[214:217], v169 offset:32768
	ds_read_b128 v[218:221], v169 offset:33792
	ds_read_b128 v[222:225], v169 offset:34816
	ds_read_b128 v[226:229], v169 offset:35840
	ds_read_b128 v[230:233], v169 offset:36864
	ds_read_b128 v[234:237], v169 offset:37888
	ds_read_b128 v[238:241], v169 offset:38912
	ds_read_b128 v[242:245], v169 offset:39936
	global_load_lds_dwordx4 v[248:249], off
	v_lshl_add_u64 v[248:249], s[10:11], 0, v[152:153]
	s_mov_b32 m0, s34
	s_nop 0
	global_load_lds_dwordx4 v[248:249], off
	s_waitcnt vmcnt(8)
	s_waitcnt lgkmcnt(0)
	s_barrier
	s_setprio 1
	v_mfma_f32_16x16x32_bf16 v[126:129], v[160:163], v[214:217], v[126:129]
	v_mfma_f32_16x16x32_bf16 v[122:125], v[186:189], v[214:217], v[122:125]
	v_mfma_f32_16x16x32_bf16 v[110:113], v[160:163], v[222:225], v[110:113]
	v_mfma_f32_16x16x32_bf16 v[106:109], v[186:189], v[222:225], v[106:109]
	v_mfma_f32_16x16x32_bf16 v[94:97], v[160:163], v[230:233], v[94:97]
	v_mfma_f32_16x16x32_bf16 v[90:93], v[186:189], v[230:233], v[90:93]
	v_mfma_f32_16x16x32_bf16 v[78:81], v[160:163], v[238:241], v[78:81]
	v_mfma_f32_16x16x32_bf16 v[74:77], v[186:189], v[238:241], v[74:77]
	v_mfma_f32_16x16x32_bf16 v[126:129], v[170:173], v[218:221], v[126:129]
	v_mfma_f32_16x16x32_bf16 v[122:125], v[190:193], v[218:221], v[122:125]
	v_mfma_f32_16x16x32_bf16 v[110:113], v[170:173], v[226:229], v[110:113]
	v_mfma_f32_16x16x32_bf16 v[106:109], v[190:193], v[226:229], v[106:109]
	v_mfma_f32_16x16x32_bf16 v[94:97], v[170:173], v[234:237], v[94:97]
	v_mfma_f32_16x16x32_bf16 v[90:93], v[190:193], v[234:237], v[90:93]
	v_mfma_f32_16x16x32_bf16 v[78:81], v[170:173], v[242:245], v[78:81]
	v_mfma_f32_16x16x32_bf16 v[74:77], v[190:193], v[242:245], v[74:77]
	s_setprio 0
	s_setprio 1
	v_mfma_f32_16x16x32_bf16 v[118:121], v[198:201], v[214:217], v[118:121]
	v_mfma_f32_16x16x32_bf16 v[114:117], v[206:209], v[214:217], v[114:117]
	v_mfma_f32_16x16x32_bf16 v[102:105], v[198:201], v[222:225], v[102:105]
	v_mfma_f32_16x16x32_bf16 v[98:101], v[206:209], v[222:225], v[98:101]
	v_mfma_f32_16x16x32_bf16 v[86:89], v[198:201], v[230:233], v[86:89]
	v_mfma_f32_16x16x32_bf16 v[82:85], v[206:209], v[230:233], v[82:85]
	v_mfma_f32_16x16x32_bf16 v[70:73], v[198:201], v[238:241], v[70:73]
	v_mfma_f32_16x16x32_bf16 v[66:69], v[206:209], v[238:241], v[66:69]
	v_mfma_f32_16x16x32_bf16 v[118:121], v[202:205], v[218:221], v[118:121]
	v_mfma_f32_16x16x32_bf16 v[114:117], v[210:213], v[218:221], v[114:117]
	v_mfma_f32_16x16x32_bf16 v[102:105], v[202:205], v[226:229], v[102:105]
	v_mfma_f32_16x16x32_bf16 v[98:101], v[210:213], v[226:229], v[98:101]
	v_mfma_f32_16x16x32_bf16 v[86:89], v[202:205], v[234:237], v[86:89]
	v_mfma_f32_16x16x32_bf16 v[82:85], v[210:213], v[234:237], v[82:85]
	v_mfma_f32_16x16x32_bf16 v[70:73], v[202:205], v[242:245], v[70:73]
	v_mfma_f32_16x16x32_bf16 v[66:69], v[210:213], v[242:245], v[66:69]
	s_setprio 0
	s_barrier
; #define PG8_STAGE(bufoff, gbase, voff) do { _Pragma("unroll") for (int _i = 0; _i < 2; ++_i) \
;         __builtin_amdgcn_global_load_lds((const unsigned*)((const char*)(gbase) + (voff)[_i]), (PG8_LAS unsigned*)(lds + (bufoff) + ldsw + _i * 8192), 16, 0, 0); } while (0)
; #define PG8_LDA(dst, b, h) do { _Pragma("unroll") for (int m = 0; m < 4; ++m) _Pragma("unroll") for (int k = 0; k < 2; ++k) dst[m][k] = *(const PG8_LAS bf16x8*)(lds + PG8_SA(b, h) + aoff + m * 2048 + k * 1024); } while (0)
; #define PG8_MMA(ai, bj, At, Bt) do { __builtin_amdgcn_s_setprio(1); _Pragma("unroll") for (int m = 0; m < 4; ++m) _Pragma("unroll") for (int n = 0; n < 2; ++n) _Pragma("unroll") for (int k = 0; k < 2; ++k) \
;         acc[ai][bj][m][n] = __builtin_amdgcn_mfma_f32_16x16x32_bf16(Bt[n][k], At[m][k], acc[ai][bj][m][n], 0, 0, 0); __builtin_amdgcn_s_setprio(0); } while (0)
; #define PG8_WAIT_V(n) asm volatile("s_waitcnt vmcnt(" #n ")" ::: "memory")
; #define PG8_WAIT_L(n) asm volatile("s_waitcnt lgkmcnt(" #n ")" ::: "memory")
; #define PG8_BAR __builtin_amdgcn_s_barrier()
; #define PG8_SCHED __builtin_amdgcn_sched_barrier(0)
; template <class Epi, class Sched, bool ALIGN_EPI = false, bool SP2 = false>
; __device__ __forceinline__ void gemm_phase(PG8_LAS unsigned char* lds, const Gemm g, const Sched& S, const Epi& E) {
;     ...
;             const bool last = (t == nt - 2);
;             const char* a1 = cA + (size_t)(t + 1) * kstep;
;             const char* a2 = last ? nA : cA + (size_t)(t + 2) * kstep; const char* b2 = last ? nB : cB + (size_t)(t + 2) * kstep;
;             const char* a3 = a2 + kstep; const char* b3 = b2 + kstep;
;     ...
;             PG8_LDA(At, 1, 1); PG8_STAGE(PG8_SB(1, 0), b3, voffB); PG8_STAGE(PG8_SB(1, 1), b3 + hstepB, voffB); PG8_STAGE(PG8_SA(1, 0), a3, voffA);
;             PG8_WAIT_V(8); PG8_WAIT_L(0); PG8_BAR; PG8_MMA(1, 0, At, B0); PG8_MMA(1, 1, At, B1); PG8_BAR; PG8_SCHED;
	s_add_i32 s10, s12, s8
	v_lshl_add_u64 v[130:131], v[130:131], 0, s[2:3]
	s_mov_b32 m0, s10
	ds_read_b128 v[214:217], v169 offset:49152
	ds_read_b128 v[218:221], v169 offset:50176
	ds_read_b128 v[222:225], v169 offset:51200
	ds_read_b128 v[226:229], v169 offset:52224
	ds_read_b128 v[230:233], v169 offset:53248
	ds_read_b128 v[234:237], v169 offset:54272
	ds_read_b128 v[238:241], v169 offset:55296
	ds_read_b128 v[242:245], v169 offset:56320
	global_load_lds_dwordx4 v[130:131], off
	s_add_i32 m0, s10, 0x2000
	s_add_u32 s10, s48, 0x100080
	v_lshl_add_u64 v[130:131], v[132:133], 0, s[2:3]
	s_addc_u32 s11, s49, 0
	s_add_i32 s12, s13, s8
	global_load_lds_dwordx4 v[130:131], off
	v_lshl_add_u64 v[130:131], s[10:11], 0, v[0:1]
	s_mov_b32 m0, s12
	s_nop 0
	global_load_lds_dwordx4 v[130:131], off
	v_lshl_add_u64 v[130:131], s[10:11], 0, v[150:151]
	s_add_i32 m0, s12, 0x2000
	s_nop 0
	global_load_lds_dwordx4 v[130:131], off
	v_lshl_add_u64 v[130:131], v[164:165], 0, s[2:3]
	s_mov_b32 m0, s35
	s_nop 0
	global_load_lds_dwordx4 v[130:131], off
	v_lshl_add_u64 v[130:131], v[246:247], 0, s[2:3]
	s_mov_b32 m0, s52
	s_nop 0
	global_load_lds_dwordx4 v[130:131], off
	s_waitcnt vmcnt(8)
	s_waitcnt lgkmcnt(0)
	s_barrier
	s_setprio 1
	v_mfma_f32_16x16x32_bf16 v[62:65], v[160:163], v[214:217], v[62:65]
	v_mfma_f32_16x16x32_bf16 v[58:61], v[186:189], v[214:217], v[58:61]
	s_add_i32 s63, s63, 2
	v_mfma_f32_16x16x32_bf16 v[46:49], v[160:163], v[222:225], v[46:49]
	s_add_u32 s46, s46, 0x100
	v_mfma_f32_16x16x32_bf16 v[42:45], v[186:189], v[222:225], v[42:45]
	s_addc_u32 s47, s47, 0
	v_mfma_f32_16x16x32_bf16 v[30:33], v[160:163], v[230:233], v[30:33]
	s_add_u32 s57, s57, 0x100
	v_mfma_f32_16x16x32_bf16 v[26:29], v[186:189], v[230:233], v[26:29]
	s_addc_u32 s62, s62, 0
	v_mfma_f32_16x16x32_bf16 v[14:17], v[160:163], v[238:241], v[14:17]
	s_add_u32 s10, s46, 0xfff00080
	v_mfma_f32_16x16x32_bf16 v[10:13], v[186:189], v[238:241], v[10:13]
	s_addc_u32 s11, s47, -1
	v_mfma_f32_16x16x32_bf16 v[62:65], v[170:173], v[218:221], v[62:65]
	s_add_i32 s12, 0, 0x10000
	v_mfma_f32_16x16x32_bf16 v[58:61], v[190:193], v[218:221], v[58:61]
	s_cmp_eq_u32 s63, 60
	v_mfma_f32_16x16x32_bf16 v[46:49], v[170:173], v[226:229], v[46:49]
	s_cselect_b32 s51, s41, s11
	v_mfma_f32_16x16x32_bf16 v[42:45], v[190:193], v[226:229], v[42:45]
	s_cselect_b32 s50, s56, s10
	v_mfma_f32_16x16x32_bf16 v[30:33], v[170:173], v[234:237], v[30:33]
	v_add_u32_e32 v130, s12, v167
	v_mfma_f32_16x16x32_bf16 v[26:29], v[190:193], v[234:237], v[26:29]
	s_cselect_b32 s49, s4, s62
	v_mfma_f32_16x16x32_bf16 v[14:17], v[170:173], v[242:245], v[14:17]
	s_cselect_b32 s48, s39, s57
	v_mfma_f32_16x16x32_bf16 v[10:13], v[190:193], v[242:245], v[10:13]
	s_add_i32 s13, 0, 0x14000
	s_setprio 0
	s_setprio 1
	v_mfma_f32_16x16x32_bf16 v[54:57], v[198:201], v[214:217], v[54:57]
	s_cmp_gt_u32 s63, 61
	v_mfma_f32_16x16x32_bf16 v[50:53], v[206:209], v[214:217], v[50:53]
	v_mfma_f32_16x16x32_bf16 v[38:41], v[198:201], v[222:225], v[38:41]
	v_mfma_f32_16x16x32_bf16 v[34:37], v[206:209], v[222:225], v[34:37]
	v_mfma_f32_16x16x32_bf16 v[22:25], v[198:201], v[230:233], v[22:25]
	v_mfma_f32_16x16x32_bf16 v[18:21], v[206:209], v[230:233], v[18:21]
	v_mfma_f32_16x16x32_bf16 v[6:9], v[198:201], v[238:241], v[6:9]
	v_mfma_f32_16x16x32_bf16 v[2:5], v[206:209], v[238:241], v[2:5]
	v_mfma_f32_16x16x32_bf16 v[54:57], v[202:205], v[218:221], v[54:57]
	v_mfma_f32_16x16x32_bf16 v[50:53], v[210:213], v[218:221], v[50:53]
	v_mfma_f32_16x16x32_bf16 v[38:41], v[202:205], v[226:229], v[38:41]
	v_mfma_f32_16x16x32_bf16 v[34:37], v[210:213], v[226:229], v[34:37]
	v_mfma_f32_16x16x32_bf16 v[22:25], v[202:205], v[234:237], v[22:25]
	v_mfma_f32_16x16x32_bf16 v[18:21], v[210:213], v[234:237], v[18:21]
	v_mfma_f32_16x16x32_bf16 v[6:9], v[202:205], v[242:245], v[6:9]
	v_mfma_f32_16x16x32_bf16 v[2:5], v[210:213], v[242:245], v[2:5]
	s_setprio 0
	s_barrier
	s_cbranch_scc0 .Lgk_929
	s_and_b64 vcc, exec, s[20:21]
	s_mov_b64 s[62:63], s[14:15]
	s_cbranch_vccz .LBB0_932
	s_barrier
